# attention steps: V fragment reads as pairs of ds_read_b64 instead of ds_read2_b64 (half the LDS cycles), lgkmcnt waits re-derived
# speedup vs baseline: 1.0029x; 1.0011x over previous
.LBB0_405:
	s_add_i32 s72, s60, -3
	s_cmp_ge_u32 s72, s38
	s_cselect_b64 s[68:69], -1, 0
	s_cmp_lt_u32 s72, s39
	s_cselect_b64 vcc, -1, 0
	s_and_b64 s[68:69], s[68:69], vcc
	s_andn2_b64 vcc, exec, s[68:69]
	s_cbranch_vccnz .LBB0_407
	v_add_u32_e32 v178, v150, v149
	v_add_u32_e32 v181, 0x2000, v178
	v_add_u32_e32 v218, 0x2800, v178
	v_add_u32_e32 v219, 0x3000, v178
	v_add_u32_e32 v178, v150, v151
	v_add_u32_e32 v119, v148, v149
	v_add_u32_e32 v136, s70, v152
	v_add_u32_sdwa v163, s70, v143 dst_sel:DWORD dst_unused:UNUSED_PAD src0_sel:DWORD src1_sel:BYTE_2
	v_add_u32_sdwa v165, s70, v143 dst_sel:DWORD dst_unused:UNUSED_PAD src0_sel:DWORD src1_sel:BYTE_3
	v_add_u32_e32 v220, 0x2000, v178
	v_add_u32_sdwa v179, s70, v141 dst_sel:DWORD dst_unused:UNUSED_PAD src0_sel:DWORD src1_sel:BYTE_1
	ds_read_b128 v[158:161], v119
	ds_read_b128 v[166:169], v119 offset:64
	ds_read_b128 v[170:173], v119 offset:2304
	ds_read_b128 v[174:177], v119 offset:2368
	v_add_u32_e32 v162, s70, v153
	ds_read_b64 v[182:183], v181 offset:1024
	ds_read_b64 v[184:185], v181 offset:1056
	ds_read_b64 v[186:187], v218 offset:1280
	ds_read_b64 v[188:189], v218 offset:1312
	ds_read_b64 v[190:191], v219 offset:1536
	ds_read_b64 v[192:193], v219 offset:1568
	ds_read_b64 v[194:195], v220 offset:1024
	ds_read_b64 v[196:197], v220 offset:1056
	ds_read_b128 v[198:201], v119 offset:1152
	ds_read_b128 v[202:205], v119 offset:1216
	ds_read_b128 v[206:209], v119 offset:3456
	ds_read_b128 v[210:213], v119 offset:3520
	v_add_u32_e32 v178, s70, v155
	v_add_u32_sdwa v214, s70, v142 dst_sel:DWORD dst_unused:UNUSED_PAD src0_sel:DWORD src1_sel:BYTE_2
	v_add_u32_sdwa v215, s70, v142 dst_sel:DWORD dst_unused:UNUSED_PAD src0_sel:DWORD src1_sel:BYTE_3
	ds_read_b32 v136, v136 offset:41856
	ds_read_b32 v216, v162 offset:41856
	ds_read_b32 v163, v163 offset:41856
	ds_read_b32 v165, v165 offset:41856
	ds_read_b32 v217, v178 offset:41856
	ds_read_b32 v179, v179 offset:41856
	ds_read_b32 v221, v214 offset:41856
	ds_read_b32 v222, v215 offset:41856
	s_setprio 1
	s_waitcnt vmcnt(7) lgkmcnt(15)
	v_mfma_f32_16x16x32_bf16 v[158:161], v[158:161], v[80:83], 0
	s_waitcnt vmcnt(6)
	v_mfma_f32_16x16x32_bf16 v[158:161], v[166:169], v[84:87], v[158:161]
	v_mfma_f32_16x16x32_bf16 v[166:169], v[170:173], v[80:83], 0
	v_mfma_f32_16x16x32_bf16 v[166:169], v[174:177], v[84:87], v[166:169]
	s_setprio 0
	s_nop 6
	v_cndmask_b32_e64 v158, v166, v158, s[20:21]
	s_waitcnt lgkmcnt(7)
	v_add_f32_e32 v136, v136, v158
	v_exp_f32_e32 v162, v136
	v_cndmask_b32_e64 v136, v159, v167, s[10:11]
	v_cndmask_b32_e64 v159, v160, v168, s[12:13]
	s_waitcnt lgkmcnt(5)
	v_add_f32_e32 v159, v163, v159
	v_add_f32_e32 v136, v216, v136
	v_exp_f32_e32 v214, v159
	v_cndmask_b32_e64 v159, v161, v169, s[14:15]
	v_exp_f32_e32 v178, v136
	s_waitcnt lgkmcnt(4)
	v_add_f32_e32 v159, v165, v159
	v_exp_f32_e32 v216, v159
	v_cndmask_b32_e64 v159, v214, 0, s[12:13]
	v_cndmask_b32_e64 v158, v178, 0, s[10:11]
	v_cndmask_b32_e64 v160, 0, v178, s[10:11]
	v_cndmask_b32_e64 v161, 0, v214, s[12:13]
	v_cndmask_b32_e64 v136, 0, v162, s[20:21]
	v_cndmask_b32_e64 v166, v162, 0, s[20:21]
	v_cndmask_b32_e64 v163, v216, 0, s[14:15]
	v_cndmask_b32_e64 v165, 0, v216, s[14:15]
	v_cvt_pk_bf16_f32 v158, v136, v158
	v_cvt_pk_bf16_f32 v159, v159, v163
	v_cvt_pk_bf16_f32 v160, v166, v160
	v_cvt_pk_bf16_f32 v161, v161, v165
	s_setprio 1
	v_mfma_f32_16x16x32_bf16 v[60:63], v[182:185], v[158:161], v[60:63]
	v_mfma_f32_16x16x32_bf16 v[56:59], v[186:189], v[158:161], v[56:59]
	v_mfma_f32_16x16x32_bf16 v[52:55], v[190:193], v[158:161], v[52:55]
	v_mfma_f32_16x16x32_bf16 v[48:51], v[194:197], v[158:161], v[48:51]
	s_setprio 0
	ds_read_b64 v[158:159], v181 offset:1040
	ds_read_b64 v[160:161], v181 offset:1072
	ds_read_b64 v[166:167], v218 offset:1296
	ds_read_b64 v[168:169], v218 offset:1328
	ds_read_b64 v[170:171], v219 offset:1552
	ds_read_b64 v[172:173], v219 offset:1584
	ds_read_b64 v[174:175], v220 offset:1040
	ds_read_b64 v[176:177], v220 offset:1072
	ds_read_b128 v[182:185], v119 offset:3456
	ds_read_b128 v[186:189], v119 offset:3520
	ds_read_b128 v[190:193], v119 offset:5760
	ds_read_b128 v[194:197], v119 offset:5824
	v_add_u32_e32 v136, s70, v156
	v_add_u32_sdwa v165, s70, v140 dst_sel:DWORD dst_unused:UNUSED_PAD src0_sel:DWORD src1_sel:BYTE_2
	v_add_u32_sdwa v163, s70, v139 dst_sel:DWORD dst_unused:UNUSED_PAD src0_sel:DWORD src1_sel:BYTE_1
	v_add_u32_sdwa v215, s70, v140 dst_sel:DWORD dst_unused:UNUSED_PAD src0_sel:DWORD src1_sel:BYTE_3
	ds_read_b32 v136, v136 offset:41856
	ds_read_b32 v223, v163 offset:41856
	ds_read_b32 v165, v165 offset:41856
	ds_read_b32 v224, v215 offset:41856
	s_setprio 1
	s_waitcnt vmcnt(5)
	v_mfma_f32_16x16x32_bf16 v[198:201], v[198:201], v[88:91], 0
	s_waitcnt vmcnt(4)
	v_mfma_f32_16x16x32_bf16 v[198:201], v[202:205], v[92:95], v[198:201]
	v_mfma_f32_16x16x32_bf16 v[202:205], v[206:209], v[88:91], 0
	v_mfma_f32_16x16x32_bf16 v[202:205], v[210:213], v[92:95], v[202:205]
	s_setprio 0
	s_nop 6
	v_cndmask_b32_e64 v163, v198, v202, s[16:17]
	s_waitcnt lgkmcnt(15)
	v_add_f32_e32 v163, v217, v163
	v_cndmask_b32_e64 v198, v199, v203, s[18:19]
	v_cndmask_b32_e64 v200, v200, v204, s[6:7]
	v_exp_f32_e32 v163, v163
	v_add_f32_e32 v179, v179, v198
	s_waitcnt lgkmcnt(15)
	v_add_f32_e32 v200, v221, v200
	v_exp_f32_e32 v179, v179
	v_exp_f32_e32 v215, v200
	v_cndmask_b32_e64 v200, v201, v205, s[8:9]
	s_waitcnt lgkmcnt(15)
	v_add_f32_e32 v200, v222, v200
	v_exp_f32_e32 v217, v200
	v_cndmask_b32_e64 v198, v163, 0, s[16:17]
	v_cndmask_b32_e64 v202, 0, v163, s[16:17]
	v_pk_add_f32 v[162:163], v[162:163], 0 op_sel_hi:[1,0]
	v_cndmask_b32_e64 v199, v179, 0, s[18:19]
	v_pk_add_f32 v[162:163], v[178:179], v[162:163]
	v_cndmask_b32_e64 v200, 0, v179, s[18:19]
	v_pk_add_f32 v[162:163], v[214:215], v[162:163]
	v_cndmask_b32_e64 v201, v215, 0, s[6:7]
	v_pk_add_f32 v[162:163], v[216:217], v[162:163]
	v_cndmask_b32_e64 v203, 0, v215, s[6:7]
	v_pk_add_f32 v[130:131], v[130:131], v[162:163]
	v_cndmask_b32_e64 v204, v217, 0, s[8:9]
	v_cndmask_b32_e64 v205, 0, v217, s[8:9]
	v_cvt_pk_bf16_f32 v198, v198, v199
	v_cvt_pk_bf16_f32 v199, v201, v204
	v_cvt_pk_bf16_f32 v200, v202, v200
	v_cvt_pk_bf16_f32 v201, v203, v205
	s_setprio 1
	s_waitcnt lgkmcnt(14)
	v_mfma_f32_16x16x32_bf16 v[44:47], v[158:161], v[198:201], v[44:47]
	s_waitcnt lgkmcnt(12)
	v_mfma_f32_16x16x32_bf16 v[40:43], v[166:169], v[198:201], v[40:43]
	s_waitcnt lgkmcnt(10)
	v_mfma_f32_16x16x32_bf16 v[36:39], v[170:173], v[198:201], v[36:39]
	s_waitcnt lgkmcnt(8)
	v_mfma_f32_16x16x32_bf16 v[32:35], v[174:177], v[198:201], v[32:35]
	s_setprio 0
	ds_read_b64 v[158:159], v181 offset:1072
	ds_read_b64 v[160:161], v181 offset:1104
	ds_read_b64 v[166:167], v218 offset:1328
	ds_read_b64 v[168:169], v218 offset:1360
	ds_read_b64 v[170:171], v219 offset:1584
	ds_read_b64 v[172:173], v219 offset:1616
	ds_read_b64 v[174:175], v220 offset:1072
	ds_read_b64 v[176:177], v220 offset:1104
	ds_read_b128 v[198:201], v119 offset:4608
	ds_read_b128 v[202:205], v119 offset:4672
	v_add_u32_e32 v119, v148, v151
	ds_read_b128 v[206:209], v119
	ds_read_b128 v[210:213], v119 offset:64
	v_add_u32_e32 v119, s70, v154
	v_add_u32_sdwa v162, s70, v144 dst_sel:DWORD dst_unused:UNUSED_PAD src0_sel:DWORD src1_sel:BYTE_1
	v_add_u32_sdwa v163, s70, v145 dst_sel:DWORD dst_unused:UNUSED_PAD src0_sel:DWORD src1_sel:BYTE_2
	v_add_u32_sdwa v178, s70, v145 dst_sel:DWORD dst_unused:UNUSED_PAD src0_sel:DWORD src1_sel:BYTE_3
	ds_read_b32 v119, v119 offset:41856
	ds_read_b32 v179, v162 offset:41856
	ds_read_b32 v214, v163 offset:41856
	ds_read_b32 v215, v178 offset:41856
	s_setprio 1
	s_waitcnt vmcnt(3) lgkmcnt(15)
	v_mfma_f32_16x16x32_bf16 v[182:185], v[182:185], v[96:99], 0
	s_waitcnt vmcnt(2)
	v_mfma_f32_16x16x32_bf16 v[182:185], v[186:189], v[100:103], v[182:185]
	v_mfma_f32_16x16x32_bf16 v[186:189], v[190:193], v[96:99], 0
	v_mfma_f32_16x16x32_bf16 v[186:189], v[194:197], v[100:103], v[186:189]
	s_setprio 0
	s_nop 6
	v_cndmask_b32_e64 v162, v186, v182, s[2:3]
	v_add_f32_e32 v136, v136, v162
	v_exp_f32_e32 v162, v136
	v_cndmask_b32_e64 v136, v187, v183, s[4:5]
	v_cndmask_b32_e64 v183, v184, v188, s[22:23]
	s_waitcnt lgkmcnt(15)
	v_add_f32_e32 v165, v165, v183
	v_exp_f32_e32 v190, v165
	v_cndmask_b32_e64 v165, v185, v189, s[24:25]
	v_add_f32_e32 v136, v223, v136
	s_waitcnt lgkmcnt(15)
	v_add_f32_e32 v165, v224, v165
	v_exp_f32_e32 v178, v136
	v_exp_f32_e32 v192, v165
	v_cndmask_b32_e64 v183, v190, 0, s[22:23]
	v_cndmask_b32_e64 v185, 0, v190, s[22:23]
	v_cndmask_b32_e64 v182, 0, v178, s[4:5]
	v_cndmask_b32_e64 v184, v192, 0, s[24:25]
	v_cndmask_b32_e64 v136, 0, v162, s[2:3]
	v_cndmask_b32_e64 v163, v162, 0, s[2:3]
	v_cndmask_b32_e64 v165, v178, 0, s[4:5]
	v_cndmask_b32_e64 v186, 0, v192, s[24:25]
	v_cvt_pk_bf16_f32 v182, v136, v182
	v_cvt_pk_bf16_f32 v183, v183, v184
	v_cvt_pk_bf16_f32 v184, v163, v165
	v_cvt_pk_bf16_f32 v185, v185, v186
	s_setprio 1
	s_waitcnt lgkmcnt(14)
	v_mfma_f32_16x16x32_bf16 v[28:31], v[158:161], v[182:185], v[28:31]
	s_waitcnt lgkmcnt(12)
	v_mfma_f32_16x16x32_bf16 v[24:27], v[166:169], v[182:185], v[24:27]
	s_waitcnt lgkmcnt(10)
	v_mfma_f32_16x16x32_bf16 v[20:23], v[170:173], v[182:185], v[20:23]
	s_waitcnt lgkmcnt(8)
	v_mfma_f32_16x16x32_bf16 v[16:19], v[174:177], v[182:185], v[16:19]
	s_setprio 0
	ds_read_b64 v[158:159], v220 offset:1088
	ds_read_b64 v[160:161], v220 offset:1120
	ds_read_b64 v[166:167], v219 offset:1600
	ds_read_b64 v[168:169], v219 offset:1632
	ds_read_b64 v[170:171], v218 offset:1344
	ds_read_b64 v[172:173], v218 offset:1376
	ds_read_b64 v[174:175], v181 offset:1088
	ds_read_b64 v[176:177], v181 offset:1120
	s_setprio 1
	s_waitcnt vmcnt(1) lgkmcnt(15)
	v_mfma_f32_16x16x32_bf16 v[182:185], v[198:201], v[104:107], 0
	s_waitcnt lgkmcnt(13)
	v_mfma_f32_16x16x32_bf16 v[186:189], v[206:209], v[104:107], 0
	s_waitcnt vmcnt(0)
	v_mfma_f32_16x16x32_bf16 v[182:185], v[202:205], v[108:111], v[182:185]
	s_waitcnt lgkmcnt(12)
	v_mfma_f32_16x16x32_bf16 v[186:189], v[210:213], v[108:111], v[186:189]
	s_setprio 0
	s_nop 6
	v_cndmask_b32_e64 v136, v182, v186, s[26:27]
	s_waitcnt lgkmcnt(11)
	v_add_f32_e32 v119, v119, v136
	v_exp_f32_e32 v163, v119
	v_cndmask_b32_e64 v119, v183, v187, s[28:29]
	v_cndmask_b32_e64 v181, v184, v188, s[30:31]
	s_waitcnt lgkmcnt(10)
	v_add_f32_e32 v119, v179, v119
	s_waitcnt lgkmcnt(9)
	v_add_f32_e32 v181, v214, v181
	v_exp_f32_e32 v179, v119
	v_exp_f32_e32 v191, v181
	v_cndmask_b32_e64 v181, v185, v189, s[34:35]
	s_waitcnt lgkmcnt(8)
	v_add_f32_e32 v181, v215, v181
	v_exp_f32_e32 v193, v181
	v_cndmask_b32_e64 v119, v163, 0, s[26:27]
	v_cndmask_b32_e64 v136, 0, v163, s[26:27]
	v_pk_add_f32 v[162:163], v[162:163], 0 op_sel_hi:[1,0]
	v_cndmask_b32_e64 v183, v191, 0, s[30:31]
	v_pk_add_f32 v[162:163], v[178:179], v[162:163]
	v_cndmask_b32_e64 v185, 0, v191, s[30:31]
	v_pk_add_f32 v[162:163], v[190:191], v[162:163]
	v_cndmask_b32_e64 v184, v193, 0, s[34:35]
	v_pk_add_f32 v[162:163], v[192:193], v[162:163]
	v_cndmask_b32_e64 v165, v179, 0, s[28:29]
	v_pk_add_f32 v[124:125], v[124:125], v[162:163]
	v_cndmask_b32_e64 v181, 0, v179, s[28:29]
	v_cndmask_b32_e64 v186, 0, v193, s[34:35]
	v_cvt_pk_bf16_f32 v182, v119, v165
	v_cvt_pk_bf16_f32 v183, v183, v184
	v_cvt_pk_bf16_f32 v184, v136, v181
	v_cvt_pk_bf16_f32 v185, v185, v186
	s_setprio 1
	s_waitcnt lgkmcnt(0)
	v_mfma_f32_16x16x32_bf16 v[12:15], v[174:177], v[182:185], v[12:15]
	v_mfma_f32_16x16x32_bf16 v[8:11], v[170:173], v[182:185], v[8:11]
	v_mfma_f32_16x16x32_bf16 v[4:7], v[166:169], v[182:185], v[4:7]
	v_mfma_f32_16x16x32_bf16 v[0:3], v[158:161], v[182:185], v[0:3]
	s_setprio 0

.LBB0_412:
	s_add_i32 s68, s60, -2
	s_cmp_ge_u32 s68, s38
	s_cselect_b64 s[72:73], -1, 0
	s_cmp_lt_u32 s68, s39
	s_cselect_b64 vcc, -1, 0
	s_and_b64 s[72:73], s[72:73], vcc
	s_andn2_b64 vcc, exec, s[72:73]
	s_cbranch_vccnz .LBB0_414
	v_add_u32_e32 v178, v150, v149
	v_add_u32_e32 v181, 0x6800, v178
	v_add_u32_e32 v218, 0x7000, v178
	v_add_u32_e32 v219, 0x7800, v178
	v_add_u32_e32 v178, v150, v151
	v_add_u32_e32 v119, v148, v149
	v_add_u32_e32 v136, s70, v152
	v_add_u32_sdwa v163, s70, v143 dst_sel:DWORD dst_unused:UNUSED_PAD src0_sel:DWORD src1_sel:BYTE_2
	v_add_u32_sdwa v165, s70, v143 dst_sel:DWORD dst_unused:UNUSED_PAD src0_sel:DWORD src1_sel:BYTE_3
	v_add_u32_e32 v220, 0x6800, v178
	v_add_u32_sdwa v179, s70, v141 dst_sel:DWORD dst_unused:UNUSED_PAD src0_sel:DWORD src1_sel:BYTE_1
	ds_read_b128 v[158:161], v119 offset:18432
	ds_read_b128 v[166:169], v119 offset:18496
	ds_read_b128 v[170:173], v119 offset:20736
	ds_read_b128 v[174:177], v119 offset:20800
	v_add_u32_e32 v162, s70, v153
	ds_read_b64 v[182:183], v181 offset:1024
	ds_read_b64 v[184:185], v181 offset:1056
	ds_read_b64 v[186:187], v218 offset:1280
	ds_read_b64 v[188:189], v218 offset:1312
	ds_read_b64 v[190:191], v219 offset:1536
	ds_read_b64 v[192:193], v219 offset:1568
	ds_read_b64 v[194:195], v220 offset:1024
	ds_read_b64 v[196:197], v220 offset:1056
	ds_read_b128 v[198:201], v119 offset:19584
	ds_read_b128 v[202:205], v119 offset:19648
	ds_read_b128 v[206:209], v119 offset:21888
	ds_read_b128 v[210:213], v119 offset:21952
	v_add_u32_e32 v178, s70, v155
	v_add_u32_sdwa v214, s70, v142 dst_sel:DWORD dst_unused:UNUSED_PAD src0_sel:DWORD src1_sel:BYTE_2
	v_add_u32_sdwa v215, s70, v142 dst_sel:DWORD dst_unused:UNUSED_PAD src0_sel:DWORD src1_sel:BYTE_3
	ds_read_b32 v136, v136 offset:41984
	ds_read_b32 v216, v162 offset:41984
	ds_read_b32 v163, v163 offset:41984
	ds_read_b32 v165, v165 offset:41984
	ds_read_b32 v217, v178 offset:41984
	ds_read_b32 v179, v179 offset:41984
	ds_read_b32 v221, v214 offset:41984
	ds_read_b32 v222, v215 offset:41984
	s_setprio 1
	s_waitcnt vmcnt(7) lgkmcnt(15)
	v_mfma_f32_16x16x32_bf16 v[158:161], v[158:161], v[80:83], 0
	s_waitcnt vmcnt(6)
	v_mfma_f32_16x16x32_bf16 v[158:161], v[166:169], v[84:87], v[158:161]
	v_mfma_f32_16x16x32_bf16 v[166:169], v[170:173], v[80:83], 0
	v_mfma_f32_16x16x32_bf16 v[166:169], v[174:177], v[84:87], v[166:169]
	s_setprio 0
	s_nop 6
	v_cndmask_b32_e64 v158, v166, v158, s[20:21]
	s_waitcnt lgkmcnt(7)
	v_add_f32_e32 v136, v136, v158
	v_exp_f32_e32 v162, v136
	v_cndmask_b32_e64 v136, v159, v167, s[10:11]
	v_cndmask_b32_e64 v159, v160, v168, s[12:13]
	s_waitcnt lgkmcnt(5)
	v_add_f32_e32 v159, v163, v159
	v_add_f32_e32 v136, v216, v136
	v_exp_f32_e32 v214, v159
	v_cndmask_b32_e64 v159, v161, v169, s[14:15]
	v_exp_f32_e32 v178, v136
	s_waitcnt lgkmcnt(4)
	v_add_f32_e32 v159, v165, v159
	v_exp_f32_e32 v216, v159
	v_cndmask_b32_e64 v159, v214, 0, s[12:13]
	v_cndmask_b32_e64 v158, v178, 0, s[10:11]
	v_cndmask_b32_e64 v160, 0, v178, s[10:11]
	v_cndmask_b32_e64 v161, 0, v214, s[12:13]
	v_cndmask_b32_e64 v136, 0, v162, s[20:21]
	v_cndmask_b32_e64 v166, v162, 0, s[20:21]
	v_cndmask_b32_e64 v163, v216, 0, s[14:15]
	v_cndmask_b32_e64 v165, 0, v216, s[14:15]
	v_cvt_pk_bf16_f32 v158, v136, v158
	v_cvt_pk_bf16_f32 v159, v159, v163
	v_cvt_pk_bf16_f32 v160, v166, v160
	v_cvt_pk_bf16_f32 v161, v161, v165
	s_setprio 1
	v_mfma_f32_16x16x32_bf16 v[60:63], v[182:185], v[158:161], v[60:63]
	v_mfma_f32_16x16x32_bf16 v[56:59], v[186:189], v[158:161], v[56:59]
	v_mfma_f32_16x16x32_bf16 v[52:55], v[190:193], v[158:161], v[52:55]
	v_mfma_f32_16x16x32_bf16 v[48:51], v[194:197], v[158:161], v[48:51]
	s_setprio 0
	ds_read_b64 v[158:159], v181 offset:1040
	ds_read_b64 v[160:161], v181 offset:1072
	ds_read_b64 v[166:167], v218 offset:1296
	ds_read_b64 v[168:169], v218 offset:1328
	ds_read_b64 v[170:171], v219 offset:1552
	ds_read_b64 v[172:173], v219 offset:1584
	ds_read_b64 v[174:175], v220 offset:1040
	ds_read_b64 v[176:177], v220 offset:1072
	ds_read_b128 v[182:185], v119 offset:21888
	ds_read_b128 v[186:189], v119 offset:21952
	ds_read_b128 v[190:193], v119 offset:24192
	ds_read_b128 v[194:197], v119 offset:24256
	v_add_u32_e32 v136, s70, v156
	v_add_u32_sdwa v165, s70, v140 dst_sel:DWORD dst_unused:UNUSED_PAD src0_sel:DWORD src1_sel:BYTE_2
	v_add_u32_sdwa v163, s70, v139 dst_sel:DWORD dst_unused:UNUSED_PAD src0_sel:DWORD src1_sel:BYTE_1
	v_add_u32_sdwa v215, s70, v140 dst_sel:DWORD dst_unused:UNUSED_PAD src0_sel:DWORD src1_sel:BYTE_3
	ds_read_b32 v136, v136 offset:41984
	ds_read_b32 v223, v163 offset:41984
	ds_read_b32 v165, v165 offset:41984
	ds_read_b32 v224, v215 offset:41984
	s_setprio 1
	s_waitcnt vmcnt(5)
	v_mfma_f32_16x16x32_bf16 v[198:201], v[198:201], v[88:91], 0
	s_waitcnt vmcnt(4)
	v_mfma_f32_16x16x32_bf16 v[198:201], v[202:205], v[92:95], v[198:201]
	v_mfma_f32_16x16x32_bf16 v[202:205], v[206:209], v[88:91], 0
	v_mfma_f32_16x16x32_bf16 v[202:205], v[210:213], v[92:95], v[202:205]
	s_setprio 0
	s_nop 6
	v_cndmask_b32_e64 v163, v198, v202, s[16:17]
	s_waitcnt lgkmcnt(15)
	v_add_f32_e32 v163, v217, v163
	v_cndmask_b32_e64 v198, v199, v203, s[18:19]
	v_cndmask_b32_e64 v200, v200, v204, s[6:7]
	v_exp_f32_e32 v163, v163
	v_add_f32_e32 v179, v179, v198
	s_waitcnt lgkmcnt(15)
	v_add_f32_e32 v200, v221, v200
	v_exp_f32_e32 v179, v179
	v_exp_f32_e32 v215, v200
	v_cndmask_b32_e64 v200, v201, v205, s[8:9]
	s_waitcnt lgkmcnt(15)
	v_add_f32_e32 v200, v222, v200
	v_exp_f32_e32 v217, v200
	v_cndmask_b32_e64 v198, v163, 0, s[16:17]
	v_cndmask_b32_e64 v202, 0, v163, s[16:17]
	v_pk_add_f32 v[162:163], v[162:163], 0 op_sel_hi:[1,0]
	v_cndmask_b32_e64 v199, v179, 0, s[18:19]
	v_pk_add_f32 v[162:163], v[178:179], v[162:163]
	v_cndmask_b32_e64 v200, 0, v179, s[18:19]
	v_pk_add_f32 v[162:163], v[214:215], v[162:163]
	v_cndmask_b32_e64 v201, v215, 0, s[6:7]
	v_pk_add_f32 v[162:163], v[216:217], v[162:163]
	v_cndmask_b32_e64 v203, 0, v215, s[6:7]
	v_pk_add_f32 v[130:131], v[130:131], v[162:163]
	v_cndmask_b32_e64 v204, v217, 0, s[8:9]
	v_cndmask_b32_e64 v205, 0, v217, s[8:9]
	v_cvt_pk_bf16_f32 v198, v198, v199
	v_cvt_pk_bf16_f32 v199, v201, v204
	v_cvt_pk_bf16_f32 v200, v202, v200
	v_cvt_pk_bf16_f32 v201, v203, v205
	s_setprio 1
	s_waitcnt lgkmcnt(14)
	v_mfma_f32_16x16x32_bf16 v[44:47], v[158:161], v[198:201], v[44:47]
	s_waitcnt lgkmcnt(12)
	v_mfma_f32_16x16x32_bf16 v[40:43], v[166:169], v[198:201], v[40:43]
	s_waitcnt lgkmcnt(10)
	v_mfma_f32_16x16x32_bf16 v[36:39], v[170:173], v[198:201], v[36:39]
	s_waitcnt lgkmcnt(8)
	v_mfma_f32_16x16x32_bf16 v[32:35], v[174:177], v[198:201], v[32:35]
	s_setprio 0
	ds_read_b64 v[158:159], v181 offset:1072
	ds_read_b64 v[160:161], v181 offset:1104
	ds_read_b64 v[166:167], v218 offset:1328
	ds_read_b64 v[168:169], v218 offset:1360
	ds_read_b64 v[170:171], v219 offset:1584
	ds_read_b64 v[172:173], v219 offset:1616
	ds_read_b64 v[174:175], v220 offset:1072
	ds_read_b64 v[176:177], v220 offset:1104
	ds_read_b128 v[198:201], v119 offset:23040
	ds_read_b128 v[202:205], v119 offset:23104
	v_add_u32_e32 v119, v148, v151
	ds_read_b128 v[206:209], v119 offset:18432
	ds_read_b128 v[210:213], v119 offset:18496
	v_add_u32_e32 v119, s70, v154
	v_add_u32_sdwa v162, s70, v144 dst_sel:DWORD dst_unused:UNUSED_PAD src0_sel:DWORD src1_sel:BYTE_1
	v_add_u32_sdwa v163, s70, v145 dst_sel:DWORD dst_unused:UNUSED_PAD src0_sel:DWORD src1_sel:BYTE_2
	v_add_u32_sdwa v178, s70, v145 dst_sel:DWORD dst_unused:UNUSED_PAD src0_sel:DWORD src1_sel:BYTE_3
	ds_read_b32 v119, v119 offset:41984
	ds_read_b32 v179, v162 offset:41984
	ds_read_b32 v214, v163 offset:41984
	ds_read_b32 v215, v178 offset:41984
	s_setprio 1
	s_waitcnt vmcnt(3) lgkmcnt(15)
	v_mfma_f32_16x16x32_bf16 v[182:185], v[182:185], v[96:99], 0
	s_waitcnt vmcnt(2)
	v_mfma_f32_16x16x32_bf16 v[182:185], v[186:189], v[100:103], v[182:185]
	v_mfma_f32_16x16x32_bf16 v[186:189], v[190:193], v[96:99], 0
	v_mfma_f32_16x16x32_bf16 v[186:189], v[194:197], v[100:103], v[186:189]
	s_setprio 0
	s_nop 6
	v_cndmask_b32_e64 v162, v186, v182, s[2:3]
	v_add_f32_e32 v136, v136, v162
	v_exp_f32_e32 v162, v136
	v_cndmask_b32_e64 v136, v187, v183, s[4:5]
	v_cndmask_b32_e64 v183, v184, v188, s[22:23]
	s_waitcnt lgkmcnt(15)
	v_add_f32_e32 v165, v165, v183
	v_exp_f32_e32 v190, v165
	v_cndmask_b32_e64 v165, v185, v189, s[24:25]
	v_add_f32_e32 v136, v223, v136
	s_waitcnt lgkmcnt(15)
	v_add_f32_e32 v165, v224, v165
	v_exp_f32_e32 v178, v136
	v_exp_f32_e32 v192, v165
	v_cndmask_b32_e64 v183, v190, 0, s[22:23]
	v_cndmask_b32_e64 v185, 0, v190, s[22:23]
	v_cndmask_b32_e64 v182, 0, v178, s[4:5]
	v_cndmask_b32_e64 v184, v192, 0, s[24:25]
	v_cndmask_b32_e64 v136, 0, v162, s[2:3]
	v_cndmask_b32_e64 v163, v162, 0, s[2:3]
	v_cndmask_b32_e64 v165, v178, 0, s[4:5]
	v_cndmask_b32_e64 v186, 0, v192, s[24:25]
	v_cvt_pk_bf16_f32 v182, v136, v182
	v_cvt_pk_bf16_f32 v183, v183, v184
	v_cvt_pk_bf16_f32 v184, v163, v165
	v_cvt_pk_bf16_f32 v185, v185, v186
	s_setprio 1
	s_waitcnt lgkmcnt(14)
	v_mfma_f32_16x16x32_bf16 v[28:31], v[158:161], v[182:185], v[28:31]
	s_waitcnt lgkmcnt(12)
	v_mfma_f32_16x16x32_bf16 v[24:27], v[166:169], v[182:185], v[24:27]
	s_waitcnt lgkmcnt(10)
	v_mfma_f32_16x16x32_bf16 v[20:23], v[170:173], v[182:185], v[20:23]
	s_waitcnt lgkmcnt(8)
	v_mfma_f32_16x16x32_bf16 v[16:19], v[174:177], v[182:185], v[16:19]
	s_setprio 0
	ds_read_b64 v[158:159], v220 offset:1088
	ds_read_b64 v[160:161], v220 offset:1120
	ds_read_b64 v[166:167], v219 offset:1600
	ds_read_b64 v[168:169], v219 offset:1632
	ds_read_b64 v[170:171], v218 offset:1344
	ds_read_b64 v[172:173], v218 offset:1376
	ds_read_b64 v[174:175], v181 offset:1088
	ds_read_b64 v[176:177], v181 offset:1120
	s_setprio 1
	s_waitcnt vmcnt(1) lgkmcnt(15)
	v_mfma_f32_16x16x32_bf16 v[182:185], v[198:201], v[104:107], 0
	s_waitcnt lgkmcnt(13)
	v_mfma_f32_16x16x32_bf16 v[186:189], v[206:209], v[104:107], 0
	s_waitcnt vmcnt(0)
	v_mfma_f32_16x16x32_bf16 v[182:185], v[202:205], v[108:111], v[182:185]
	s_waitcnt lgkmcnt(12)
	v_mfma_f32_16x16x32_bf16 v[186:189], v[210:213], v[108:111], v[186:189]
	s_setprio 0
	s_nop 6
	v_cndmask_b32_e64 v136, v182, v186, s[26:27]
	s_waitcnt lgkmcnt(11)
	v_add_f32_e32 v119, v119, v136
	v_exp_f32_e32 v163, v119
	v_cndmask_b32_e64 v119, v183, v187, s[28:29]
	v_cndmask_b32_e64 v181, v184, v188, s[30:31]
	s_waitcnt lgkmcnt(10)
	v_add_f32_e32 v119, v179, v119
	s_waitcnt lgkmcnt(9)
	v_add_f32_e32 v181, v214, v181
	v_exp_f32_e32 v179, v119
	v_exp_f32_e32 v191, v181
	v_cndmask_b32_e64 v181, v185, v189, s[34:35]
	s_waitcnt lgkmcnt(8)
	v_add_f32_e32 v181, v215, v181
	v_exp_f32_e32 v193, v181
	v_cndmask_b32_e64 v119, v163, 0, s[26:27]
	v_cndmask_b32_e64 v136, 0, v163, s[26:27]
	v_pk_add_f32 v[162:163], v[162:163], 0 op_sel_hi:[1,0]
	v_cndmask_b32_e64 v183, v191, 0, s[30:31]
	v_pk_add_f32 v[162:163], v[178:179], v[162:163]
	v_cndmask_b32_e64 v185, 0, v191, s[30:31]
	v_pk_add_f32 v[162:163], v[190:191], v[162:163]
	v_cndmask_b32_e64 v184, v193, 0, s[34:35]
	v_pk_add_f32 v[162:163], v[192:193], v[162:163]
	v_cndmask_b32_e64 v165, v179, 0, s[28:29]
	v_pk_add_f32 v[124:125], v[124:125], v[162:163]
	v_cndmask_b32_e64 v181, 0, v179, s[28:29]
	v_cndmask_b32_e64 v186, 0, v193, s[34:35]
	v_cvt_pk_bf16_f32 v182, v119, v165
	v_cvt_pk_bf16_f32 v183, v183, v184
	v_cvt_pk_bf16_f32 v184, v136, v181
	v_cvt_pk_bf16_f32 v185, v185, v186
	s_setprio 1
	s_waitcnt lgkmcnt(0)
	v_mfma_f32_16x16x32_bf16 v[12:15], v[174:177], v[182:185], v[12:15]
	v_mfma_f32_16x16x32_bf16 v[8:11], v[170:173], v[182:185], v[8:11]
	v_mfma_f32_16x16x32_bf16 v[4:7], v[166:169], v[182:185], v[4:7]
	v_mfma_f32_16x16x32_bf16 v[0:3], v[158:161], v[182:185], v[0:3]
	s_setprio 0

.LBB0_489:
	s_add_i32 s68, s48, -3
	s_cmp_ge_u32 s68, s38
	s_cselect_b64 s[64:65], -1, 0
	s_cmp_lt_u32 s68, s39
	s_cselect_b64 s[94:95], -1, 0
	s_and_b64 s[64:65], s[64:65], s[94:95]
	s_andn2_b64 vcc, exec, s[64:65]
	s_cbranch_vccnz .LBB0_491
	v_add_u32_e32 v178, v150, v149
	v_add_u32_e32 v181, 0x2000, v178
	v_add_u32_e32 v218, 0x2800, v178
	v_add_u32_e32 v219, 0x3000, v178
	v_add_u32_e32 v178, v150, v151
	v_add_u32_e32 v119, v148, v149
	v_add_u32_e32 v136, s66, v152
	v_add_u32_sdwa v163, s66, v143 dst_sel:DWORD dst_unused:UNUSED_PAD src0_sel:DWORD src1_sel:BYTE_2
	v_add_u32_sdwa v165, s66, v143 dst_sel:DWORD dst_unused:UNUSED_PAD src0_sel:DWORD src1_sel:BYTE_3
	v_add_u32_e32 v220, 0x2000, v178
	v_add_u32_sdwa v179, s66, v141 dst_sel:DWORD dst_unused:UNUSED_PAD src0_sel:DWORD src1_sel:BYTE_1
	ds_read_b128 v[158:161], v119
	ds_read_b128 v[166:169], v119 offset:64
	ds_read_b128 v[170:173], v119 offset:2304
	ds_read_b128 v[174:177], v119 offset:2368
	v_add_u32_e32 v162, s66, v153
	ds_read_b64 v[182:183], v181 offset:1024
	ds_read_b64 v[184:185], v181 offset:1056
	ds_read_b64 v[186:187], v218 offset:1280
	ds_read_b64 v[188:189], v218 offset:1312
	ds_read_b64 v[190:191], v219 offset:1536
	ds_read_b64 v[192:193], v219 offset:1568
	ds_read_b64 v[194:195], v220 offset:1024
	ds_read_b64 v[196:197], v220 offset:1056
	ds_read_b128 v[198:201], v119 offset:1152
	ds_read_b128 v[202:205], v119 offset:1216
	ds_read_b128 v[206:209], v119 offset:3456
	ds_read_b128 v[210:213], v119 offset:3520
	v_add_u32_e32 v178, s66, v155
	v_add_u32_sdwa v214, s66, v142 dst_sel:DWORD dst_unused:UNUSED_PAD src0_sel:DWORD src1_sel:BYTE_2
	v_add_u32_sdwa v215, s66, v142 dst_sel:DWORD dst_unused:UNUSED_PAD src0_sel:DWORD src1_sel:BYTE_3
	ds_read_b32 v136, v136 offset:41856
	ds_read_b32 v216, v162 offset:41856
	ds_read_b32 v163, v163 offset:41856
	ds_read_b32 v165, v165 offset:41856
	ds_read_b32 v217, v178 offset:41856
	ds_read_b32 v179, v179 offset:41856
	ds_read_b32 v221, v214 offset:41856
	ds_read_b32 v222, v215 offset:41856
	s_setprio 1
	s_waitcnt vmcnt(7) lgkmcnt(15)
	v_mfma_f32_16x16x32_bf16 v[158:161], v[158:161], v[80:83], 0
	s_waitcnt vmcnt(6)
	v_mfma_f32_16x16x32_bf16 v[158:161], v[166:169], v[84:87], v[158:161]
	v_mfma_f32_16x16x32_bf16 v[166:169], v[170:173], v[80:83], 0
	v_mfma_f32_16x16x32_bf16 v[166:169], v[174:177], v[84:87], v[166:169]
	s_setprio 0
	s_nop 6
	v_cndmask_b32_e64 v158, v166, v158, s[20:21]
	s_waitcnt lgkmcnt(7)
	v_add_f32_e32 v136, v136, v158
	v_exp_f32_e32 v162, v136
	v_cndmask_b32_e64 v136, v159, v167, s[10:11]
	v_cndmask_b32_e64 v159, v160, v168, s[12:13]
	s_waitcnt lgkmcnt(5)
	v_add_f32_e32 v159, v163, v159
	v_add_f32_e32 v136, v216, v136
	v_exp_f32_e32 v214, v159
	v_cndmask_b32_e64 v159, v161, v169, s[14:15]
	v_exp_f32_e32 v178, v136
	s_waitcnt lgkmcnt(4)
	v_add_f32_e32 v159, v165, v159
	v_exp_f32_e32 v216, v159
	v_cndmask_b32_e64 v159, v214, 0, s[12:13]
	v_cndmask_b32_e64 v158, v178, 0, s[10:11]
	v_cndmask_b32_e64 v160, 0, v178, s[10:11]
	v_cndmask_b32_e64 v161, 0, v214, s[12:13]
	v_cndmask_b32_e64 v136, 0, v162, s[20:21]
	v_cndmask_b32_e64 v166, v162, 0, s[20:21]
	v_cndmask_b32_e64 v163, v216, 0, s[14:15]
	v_cndmask_b32_e64 v165, 0, v216, s[14:15]
	v_cvt_pk_bf16_f32 v158, v136, v158
	v_cvt_pk_bf16_f32 v159, v159, v163
	v_cvt_pk_bf16_f32 v160, v166, v160
	v_cvt_pk_bf16_f32 v161, v161, v165
	s_setprio 1
	v_mfma_f32_16x16x32_bf16 v[60:63], v[182:185], v[158:161], v[60:63]
	v_mfma_f32_16x16x32_bf16 v[56:59], v[186:189], v[158:161], v[56:59]
	v_mfma_f32_16x16x32_bf16 v[52:55], v[190:193], v[158:161], v[52:55]
	v_mfma_f32_16x16x32_bf16 v[48:51], v[194:197], v[158:161], v[48:51]
	s_setprio 0
	ds_read_b64 v[158:159], v181 offset:1040
	ds_read_b64 v[160:161], v181 offset:1072
	ds_read_b64 v[166:167], v218 offset:1296
	ds_read_b64 v[168:169], v218 offset:1328
	ds_read_b64 v[170:171], v219 offset:1552
	ds_read_b64 v[172:173], v219 offset:1584
	ds_read_b64 v[174:175], v220 offset:1040
	ds_read_b64 v[176:177], v220 offset:1072
	ds_read_b128 v[182:185], v119 offset:3456
	ds_read_b128 v[186:189], v119 offset:3520
	ds_read_b128 v[190:193], v119 offset:5760
	ds_read_b128 v[194:197], v119 offset:5824
	v_add_u32_e32 v136, s66, v156
	v_add_u32_sdwa v165, s66, v140 dst_sel:DWORD dst_unused:UNUSED_PAD src0_sel:DWORD src1_sel:BYTE_2
	v_add_u32_sdwa v163, s66, v139 dst_sel:DWORD dst_unused:UNUSED_PAD src0_sel:DWORD src1_sel:BYTE_1
	v_add_u32_sdwa v215, s66, v140 dst_sel:DWORD dst_unused:UNUSED_PAD src0_sel:DWORD src1_sel:BYTE_3
	ds_read_b32 v136, v136 offset:41856
	ds_read_b32 v223, v163 offset:41856
	ds_read_b32 v165, v165 offset:41856
	ds_read_b32 v224, v215 offset:41856
	s_setprio 1
	s_waitcnt vmcnt(5)
	v_mfma_f32_16x16x32_bf16 v[198:201], v[198:201], v[88:91], 0
	s_waitcnt vmcnt(4)
	v_mfma_f32_16x16x32_bf16 v[198:201], v[202:205], v[92:95], v[198:201]
	v_mfma_f32_16x16x32_bf16 v[202:205], v[206:209], v[88:91], 0
	v_mfma_f32_16x16x32_bf16 v[202:205], v[210:213], v[92:95], v[202:205]
	s_setprio 0
	s_nop 6
	v_cndmask_b32_e64 v163, v198, v202, s[16:17]
	s_waitcnt lgkmcnt(15)
	v_add_f32_e32 v163, v217, v163
	v_cndmask_b32_e64 v198, v199, v203, s[18:19]
	v_cndmask_b32_e64 v200, v200, v204, s[6:7]
	v_exp_f32_e32 v163, v163
	v_add_f32_e32 v179, v179, v198
	s_waitcnt lgkmcnt(15)
	v_add_f32_e32 v200, v221, v200
	v_exp_f32_e32 v179, v179
	v_exp_f32_e32 v215, v200
	v_cndmask_b32_e64 v200, v201, v205, s[8:9]
	s_waitcnt lgkmcnt(15)
	v_add_f32_e32 v200, v222, v200
	v_exp_f32_e32 v217, v200
	v_cndmask_b32_e64 v198, v163, 0, s[16:17]
	v_cndmask_b32_e64 v202, 0, v163, s[16:17]
	v_pk_add_f32 v[162:163], v[162:163], 0 op_sel_hi:[1,0]
	v_cndmask_b32_e64 v199, v179, 0, s[18:19]
	v_pk_add_f32 v[162:163], v[178:179], v[162:163]
	v_cndmask_b32_e64 v200, 0, v179, s[18:19]
	v_pk_add_f32 v[162:163], v[214:215], v[162:163]
	v_cndmask_b32_e64 v201, v215, 0, s[6:7]
	v_pk_add_f32 v[162:163], v[216:217], v[162:163]
	v_cndmask_b32_e64 v203, 0, v215, s[6:7]
	v_pk_add_f32 v[130:131], v[130:131], v[162:163]
	v_cndmask_b32_e64 v204, v217, 0, s[8:9]
	v_cndmask_b32_e64 v205, 0, v217, s[8:9]
	v_cvt_pk_bf16_f32 v198, v198, v199
	v_cvt_pk_bf16_f32 v199, v201, v204
	v_cvt_pk_bf16_f32 v200, v202, v200
	v_cvt_pk_bf16_f32 v201, v203, v205
	s_setprio 1
	s_waitcnt lgkmcnt(14)
	v_mfma_f32_16x16x32_bf16 v[44:47], v[158:161], v[198:201], v[44:47]
	s_waitcnt lgkmcnt(12)
	v_mfma_f32_16x16x32_bf16 v[40:43], v[166:169], v[198:201], v[40:43]
	s_waitcnt lgkmcnt(10)
	v_mfma_f32_16x16x32_bf16 v[36:39], v[170:173], v[198:201], v[36:39]
	s_waitcnt lgkmcnt(8)
	v_mfma_f32_16x16x32_bf16 v[32:35], v[174:177], v[198:201], v[32:35]
	s_setprio 0
	ds_read_b64 v[158:159], v181 offset:1072
	ds_read_b64 v[160:161], v181 offset:1104
	ds_read_b64 v[166:167], v218 offset:1328
	ds_read_b64 v[168:169], v218 offset:1360
	ds_read_b64 v[170:171], v219 offset:1584
	ds_read_b64 v[172:173], v219 offset:1616
	ds_read_b64 v[174:175], v220 offset:1072
	ds_read_b64 v[176:177], v220 offset:1104
	ds_read_b128 v[198:201], v119 offset:4608
	ds_read_b128 v[202:205], v119 offset:4672
	v_add_u32_e32 v119, v148, v151
	ds_read_b128 v[206:209], v119
	ds_read_b128 v[210:213], v119 offset:64
	v_add_u32_e32 v119, s66, v154
	v_add_u32_sdwa v162, s66, v144 dst_sel:DWORD dst_unused:UNUSED_PAD src0_sel:DWORD src1_sel:BYTE_1
	v_add_u32_sdwa v163, s66, v145 dst_sel:DWORD dst_unused:UNUSED_PAD src0_sel:DWORD src1_sel:BYTE_2
	v_add_u32_sdwa v178, s66, v145 dst_sel:DWORD dst_unused:UNUSED_PAD src0_sel:DWORD src1_sel:BYTE_3
	ds_read_b32 v119, v119 offset:41856
	ds_read_b32 v179, v162 offset:41856
	ds_read_b32 v214, v163 offset:41856
	ds_read_b32 v215, v178 offset:41856
	s_setprio 1
	s_waitcnt vmcnt(3) lgkmcnt(15)
	v_mfma_f32_16x16x32_bf16 v[182:185], v[182:185], v[96:99], 0
	s_waitcnt vmcnt(2)
	v_mfma_f32_16x16x32_bf16 v[182:185], v[186:189], v[100:103], v[182:185]
	v_mfma_f32_16x16x32_bf16 v[186:189], v[190:193], v[96:99], 0
	v_mfma_f32_16x16x32_bf16 v[186:189], v[194:197], v[100:103], v[186:189]
	s_setprio 0
	s_nop 6
	v_cndmask_b32_e64 v162, v186, v182, s[2:3]
	v_add_f32_e32 v136, v136, v162
	v_exp_f32_e32 v162, v136
	v_cndmask_b32_e64 v136, v187, v183, s[4:5]
	v_cndmask_b32_e64 v183, v184, v188, s[22:23]
	s_waitcnt lgkmcnt(15)
	v_add_f32_e32 v165, v165, v183
	v_exp_f32_e32 v190, v165
	v_cndmask_b32_e64 v165, v185, v189, s[24:25]
	v_add_f32_e32 v136, v223, v136
	s_waitcnt lgkmcnt(15)
	v_add_f32_e32 v165, v224, v165
	v_exp_f32_e32 v178, v136
	v_exp_f32_e32 v192, v165
	v_cndmask_b32_e64 v183, v190, 0, s[22:23]
	v_cndmask_b32_e64 v185, 0, v190, s[22:23]
	v_cndmask_b32_e64 v182, 0, v178, s[4:5]
	v_cndmask_b32_e64 v184, v192, 0, s[24:25]
	v_cndmask_b32_e64 v136, 0, v162, s[2:3]
	v_cndmask_b32_e64 v163, v162, 0, s[2:3]
	v_cndmask_b32_e64 v165, v178, 0, s[4:5]
	v_cndmask_b32_e64 v186, 0, v192, s[24:25]
	v_cvt_pk_bf16_f32 v182, v136, v182
	v_cvt_pk_bf16_f32 v183, v183, v184
	v_cvt_pk_bf16_f32 v184, v163, v165
	v_cvt_pk_bf16_f32 v185, v185, v186
	s_setprio 1
	s_waitcnt lgkmcnt(14)
	v_mfma_f32_16x16x32_bf16 v[28:31], v[158:161], v[182:185], v[28:31]
	s_waitcnt lgkmcnt(12)
	v_mfma_f32_16x16x32_bf16 v[24:27], v[166:169], v[182:185], v[24:27]
	s_waitcnt lgkmcnt(10)
	v_mfma_f32_16x16x32_bf16 v[20:23], v[170:173], v[182:185], v[20:23]
	s_waitcnt lgkmcnt(8)
	v_mfma_f32_16x16x32_bf16 v[16:19], v[174:177], v[182:185], v[16:19]
	s_setprio 0
	ds_read_b64 v[158:159], v220 offset:1088
	ds_read_b64 v[160:161], v220 offset:1120
	ds_read_b64 v[166:167], v219 offset:1600
	ds_read_b64 v[168:169], v219 offset:1632
	ds_read_b64 v[170:171], v218 offset:1344
	ds_read_b64 v[172:173], v218 offset:1376
	ds_read_b64 v[174:175], v181 offset:1088
	ds_read_b64 v[176:177], v181 offset:1120
	s_setprio 1
	s_waitcnt vmcnt(1) lgkmcnt(15)
	v_mfma_f32_16x16x32_bf16 v[182:185], v[198:201], v[104:107], 0
	s_waitcnt lgkmcnt(13)
	v_mfma_f32_16x16x32_bf16 v[186:189], v[206:209], v[104:107], 0
	s_waitcnt vmcnt(0)
	v_mfma_f32_16x16x32_bf16 v[182:185], v[202:205], v[108:111], v[182:185]
	s_waitcnt lgkmcnt(12)
	v_mfma_f32_16x16x32_bf16 v[186:189], v[210:213], v[108:111], v[186:189]
	s_setprio 0
	s_nop 6
	v_cndmask_b32_e64 v136, v182, v186, s[26:27]
	s_waitcnt lgkmcnt(11)
	v_add_f32_e32 v119, v119, v136
	v_exp_f32_e32 v163, v119
	v_cndmask_b32_e64 v119, v183, v187, s[28:29]
	v_cndmask_b32_e64 v181, v184, v188, s[30:31]
	s_waitcnt lgkmcnt(10)
	v_add_f32_e32 v119, v179, v119
	s_waitcnt lgkmcnt(9)
	v_add_f32_e32 v181, v214, v181
	v_exp_f32_e32 v179, v119
	v_exp_f32_e32 v191, v181
	v_cndmask_b32_e64 v181, v185, v189, s[34:35]
	s_waitcnt lgkmcnt(8)
	v_add_f32_e32 v181, v215, v181
	v_exp_f32_e32 v193, v181
	v_cndmask_b32_e64 v119, v163, 0, s[26:27]
	v_cndmask_b32_e64 v136, 0, v163, s[26:27]
	v_pk_add_f32 v[162:163], v[162:163], 0 op_sel_hi:[1,0]
	v_cndmask_b32_e64 v183, v191, 0, s[30:31]
	v_pk_add_f32 v[162:163], v[178:179], v[162:163]
	v_cndmask_b32_e64 v185, 0, v191, s[30:31]
	v_pk_add_f32 v[162:163], v[190:191], v[162:163]
	v_cndmask_b32_e64 v184, v193, 0, s[34:35]
	v_pk_add_f32 v[162:163], v[192:193], v[162:163]
	v_cndmask_b32_e64 v165, v179, 0, s[28:29]
	v_pk_add_f32 v[124:125], v[124:125], v[162:163]
	v_cndmask_b32_e64 v181, 0, v179, s[28:29]
	v_cndmask_b32_e64 v186, 0, v193, s[34:35]
	v_cvt_pk_bf16_f32 v182, v119, v165
	v_cvt_pk_bf16_f32 v183, v183, v184
	v_cvt_pk_bf16_f32 v184, v136, v181
	v_cvt_pk_bf16_f32 v185, v185, v186
	s_setprio 1
	s_waitcnt lgkmcnt(0)
	v_mfma_f32_16x16x32_bf16 v[12:15], v[174:177], v[182:185], v[12:15]
	v_mfma_f32_16x16x32_bf16 v[8:11], v[170:173], v[182:185], v[8:11]
	v_mfma_f32_16x16x32_bf16 v[4:7], v[166:169], v[182:185], v[4:7]
	v_mfma_f32_16x16x32_bf16 v[0:3], v[158:161], v[182:185], v[0:3]
	s_setprio 0

.LBB0_496:
	s_add_i32 s64, s48, -2
	s_cmp_ge_u32 s64, s38
	s_cselect_b64 s[68:69], -1, 0
	s_cmp_lt_u32 s64, s39
	s_cselect_b64 s[94:95], -1, 0
	s_and_b64 s[68:69], s[68:69], s[94:95]
	s_andn2_b64 vcc, exec, s[68:69]
	s_cbranch_vccnz .LBB0_498
	v_add_u32_e32 v178, v150, v149
	v_add_u32_e32 v181, 0x6800, v178
	v_add_u32_e32 v218, 0x7000, v178
	v_add_u32_e32 v219, 0x7800, v178
	v_add_u32_e32 v178, v150, v151
	v_add_u32_e32 v119, v148, v149
	v_add_u32_e32 v136, s66, v152
	v_add_u32_sdwa v163, s66, v143 dst_sel:DWORD dst_unused:UNUSED_PAD src0_sel:DWORD src1_sel:BYTE_2
	v_add_u32_sdwa v165, s66, v143 dst_sel:DWORD dst_unused:UNUSED_PAD src0_sel:DWORD src1_sel:BYTE_3
	v_add_u32_e32 v220, 0x6800, v178
	v_add_u32_sdwa v179, s66, v141 dst_sel:DWORD dst_unused:UNUSED_PAD src0_sel:DWORD src1_sel:BYTE_1
	ds_read_b128 v[158:161], v119 offset:18432
	ds_read_b128 v[166:169], v119 offset:18496
	ds_read_b128 v[170:173], v119 offset:20736
	ds_read_b128 v[174:177], v119 offset:20800
	v_add_u32_e32 v162, s66, v153
	ds_read_b64 v[182:183], v181 offset:1024
	ds_read_b64 v[184:185], v181 offset:1056
	ds_read_b64 v[186:187], v218 offset:1280
	ds_read_b64 v[188:189], v218 offset:1312
	ds_read_b64 v[190:191], v219 offset:1536
	ds_read_b64 v[192:193], v219 offset:1568
	ds_read_b64 v[194:195], v220 offset:1024
	ds_read_b64 v[196:197], v220 offset:1056
	ds_read_b128 v[198:201], v119 offset:19584
	ds_read_b128 v[202:205], v119 offset:19648
	ds_read_b128 v[206:209], v119 offset:21888
	ds_read_b128 v[210:213], v119 offset:21952
	v_add_u32_e32 v178, s66, v155
	v_add_u32_sdwa v214, s66, v142 dst_sel:DWORD dst_unused:UNUSED_PAD src0_sel:DWORD src1_sel:BYTE_2
	v_add_u32_sdwa v215, s66, v142 dst_sel:DWORD dst_unused:UNUSED_PAD src0_sel:DWORD src1_sel:BYTE_3
	ds_read_b32 v136, v136 offset:41984
	ds_read_b32 v216, v162 offset:41984
	ds_read_b32 v163, v163 offset:41984
	ds_read_b32 v165, v165 offset:41984
	ds_read_b32 v217, v178 offset:41984
	ds_read_b32 v179, v179 offset:41984
	ds_read_b32 v221, v214 offset:41984
	ds_read_b32 v222, v215 offset:41984
	s_setprio 1
	s_waitcnt vmcnt(7) lgkmcnt(15)
	v_mfma_f32_16x16x32_bf16 v[158:161], v[158:161], v[80:83], 0
	s_waitcnt vmcnt(6)
	v_mfma_f32_16x16x32_bf16 v[158:161], v[166:169], v[84:87], v[158:161]
	v_mfma_f32_16x16x32_bf16 v[166:169], v[170:173], v[80:83], 0
	v_mfma_f32_16x16x32_bf16 v[166:169], v[174:177], v[84:87], v[166:169]
	s_setprio 0
	s_nop 6
	v_cndmask_b32_e64 v158, v166, v158, s[20:21]
	s_waitcnt lgkmcnt(7)
	v_add_f32_e32 v136, v136, v158
	v_exp_f32_e32 v162, v136
	v_cndmask_b32_e64 v136, v159, v167, s[10:11]
	v_cndmask_b32_e64 v159, v160, v168, s[12:13]
	s_waitcnt lgkmcnt(5)
	v_add_f32_e32 v159, v163, v159
	v_add_f32_e32 v136, v216, v136
	v_exp_f32_e32 v214, v159
	v_cndmask_b32_e64 v159, v161, v169, s[14:15]
	v_exp_f32_e32 v178, v136
	s_waitcnt lgkmcnt(4)
	v_add_f32_e32 v159, v165, v159
	v_exp_f32_e32 v216, v159
	v_cndmask_b32_e64 v159, v214, 0, s[12:13]
	v_cndmask_b32_e64 v158, v178, 0, s[10:11]
	v_cndmask_b32_e64 v160, 0, v178, s[10:11]
	v_cndmask_b32_e64 v161, 0, v214, s[12:13]
	v_cndmask_b32_e64 v136, 0, v162, s[20:21]
	v_cndmask_b32_e64 v166, v162, 0, s[20:21]
	v_cndmask_b32_e64 v163, v216, 0, s[14:15]
	v_cndmask_b32_e64 v165, 0, v216, s[14:15]
	v_cvt_pk_bf16_f32 v158, v136, v158
	v_cvt_pk_bf16_f32 v159, v159, v163
	v_cvt_pk_bf16_f32 v160, v166, v160
	v_cvt_pk_bf16_f32 v161, v161, v165
	s_setprio 1
	v_mfma_f32_16x16x32_bf16 v[60:63], v[182:185], v[158:161], v[60:63]
	v_mfma_f32_16x16x32_bf16 v[56:59], v[186:189], v[158:161], v[56:59]
	v_mfma_f32_16x16x32_bf16 v[52:55], v[190:193], v[158:161], v[52:55]
	v_mfma_f32_16x16x32_bf16 v[48:51], v[194:197], v[158:161], v[48:51]
	s_setprio 0
	ds_read_b64 v[158:159], v181 offset:1040
	ds_read_b64 v[160:161], v181 offset:1072
	ds_read_b64 v[166:167], v218 offset:1296
	ds_read_b64 v[168:169], v218 offset:1328
	ds_read_b64 v[170:171], v219 offset:1552
	ds_read_b64 v[172:173], v219 offset:1584
	ds_read_b64 v[174:175], v220 offset:1040
	ds_read_b64 v[176:177], v220 offset:1072
	ds_read_b128 v[182:185], v119 offset:21888
	ds_read_b128 v[186:189], v119 offset:21952
	ds_read_b128 v[190:193], v119 offset:24192
	ds_read_b128 v[194:197], v119 offset:24256
	v_add_u32_e32 v136, s66, v156
	v_add_u32_sdwa v165, s66, v140 dst_sel:DWORD dst_unused:UNUSED_PAD src0_sel:DWORD src1_sel:BYTE_2
	v_add_u32_sdwa v163, s66, v139 dst_sel:DWORD dst_unused:UNUSED_PAD src0_sel:DWORD src1_sel:BYTE_1
	v_add_u32_sdwa v215, s66, v140 dst_sel:DWORD dst_unused:UNUSED_PAD src0_sel:DWORD src1_sel:BYTE_3
	ds_read_b32 v136, v136 offset:41984
	ds_read_b32 v223, v163 offset:41984
	ds_read_b32 v165, v165 offset:41984
	ds_read_b32 v224, v215 offset:41984
	s_setprio 1
	s_waitcnt vmcnt(5)
	v_mfma_f32_16x16x32_bf16 v[198:201], v[198:201], v[88:91], 0
	s_waitcnt vmcnt(4)
	v_mfma_f32_16x16x32_bf16 v[198:201], v[202:205], v[92:95], v[198:201]
	v_mfma_f32_16x16x32_bf16 v[202:205], v[206:209], v[88:91], 0
	v_mfma_f32_16x16x32_bf16 v[202:205], v[210:213], v[92:95], v[202:205]
	s_setprio 0
	s_nop 6
	v_cndmask_b32_e64 v163, v198, v202, s[16:17]
	s_waitcnt lgkmcnt(15)
	v_add_f32_e32 v163, v217, v163
	v_cndmask_b32_e64 v198, v199, v203, s[18:19]
	v_cndmask_b32_e64 v200, v200, v204, s[6:7]
	v_exp_f32_e32 v163, v163
	v_add_f32_e32 v179, v179, v198
	s_waitcnt lgkmcnt(15)
	v_add_f32_e32 v200, v221, v200
	v_exp_f32_e32 v179, v179
	v_exp_f32_e32 v215, v200
	v_cndmask_b32_e64 v200, v201, v205, s[8:9]
	s_waitcnt lgkmcnt(15)
	v_add_f32_e32 v200, v222, v200
	v_exp_f32_e32 v217, v200
	v_cndmask_b32_e64 v198, v163, 0, s[16:17]
	v_cndmask_b32_e64 v202, 0, v163, s[16:17]
	v_pk_add_f32 v[162:163], v[162:163], 0 op_sel_hi:[1,0]
	v_cndmask_b32_e64 v199, v179, 0, s[18:19]
	v_pk_add_f32 v[162:163], v[178:179], v[162:163]
	v_cndmask_b32_e64 v200, 0, v179, s[18:19]
	v_pk_add_f32 v[162:163], v[214:215], v[162:163]
	v_cndmask_b32_e64 v201, v215, 0, s[6:7]
	v_pk_add_f32 v[162:163], v[216:217], v[162:163]
	v_cndmask_b32_e64 v203, 0, v215, s[6:7]
	v_pk_add_f32 v[130:131], v[130:131], v[162:163]
	v_cndmask_b32_e64 v204, v217, 0, s[8:9]
	v_cndmask_b32_e64 v205, 0, v217, s[8:9]
	v_cvt_pk_bf16_f32 v198, v198, v199
	v_cvt_pk_bf16_f32 v199, v201, v204
	v_cvt_pk_bf16_f32 v200, v202, v200
	v_cvt_pk_bf16_f32 v201, v203, v205
	s_setprio 1
	s_waitcnt lgkmcnt(14)
	v_mfma_f32_16x16x32_bf16 v[44:47], v[158:161], v[198:201], v[44:47]
	s_waitcnt lgkmcnt(12)
	v_mfma_f32_16x16x32_bf16 v[40:43], v[166:169], v[198:201], v[40:43]
	s_waitcnt lgkmcnt(10)
	v_mfma_f32_16x16x32_bf16 v[36:39], v[170:173], v[198:201], v[36:39]
	s_waitcnt lgkmcnt(8)
	v_mfma_f32_16x16x32_bf16 v[32:35], v[174:177], v[198:201], v[32:35]
	s_setprio 0
	ds_read_b64 v[158:159], v181 offset:1072
	ds_read_b64 v[160:161], v181 offset:1104
	ds_read_b64 v[166:167], v218 offset:1328
	ds_read_b64 v[168:169], v218 offset:1360
	ds_read_b64 v[170:171], v219 offset:1584
	ds_read_b64 v[172:173], v219 offset:1616
	ds_read_b64 v[174:175], v220 offset:1072
	ds_read_b64 v[176:177], v220 offset:1104
	ds_read_b128 v[198:201], v119 offset:23040
	ds_read_b128 v[202:205], v119 offset:23104
	v_add_u32_e32 v119, v148, v151
	ds_read_b128 v[206:209], v119 offset:18432
	ds_read_b128 v[210:213], v119 offset:18496
	v_add_u32_e32 v119, s66, v154
	v_add_u32_sdwa v162, s66, v144 dst_sel:DWORD dst_unused:UNUSED_PAD src0_sel:DWORD src1_sel:BYTE_1
	v_add_u32_sdwa v163, s66, v145 dst_sel:DWORD dst_unused:UNUSED_PAD src0_sel:DWORD src1_sel:BYTE_2
	v_add_u32_sdwa v178, s66, v145 dst_sel:DWORD dst_unused:UNUSED_PAD src0_sel:DWORD src1_sel:BYTE_3
	ds_read_b32 v119, v119 offset:41984
	ds_read_b32 v179, v162 offset:41984
	ds_read_b32 v214, v163 offset:41984
	ds_read_b32 v215, v178 offset:41984
	s_setprio 1
	s_waitcnt vmcnt(3) lgkmcnt(15)
	v_mfma_f32_16x16x32_bf16 v[182:185], v[182:185], v[96:99], 0
	s_waitcnt vmcnt(2)
	v_mfma_f32_16x16x32_bf16 v[182:185], v[186:189], v[100:103], v[182:185]
	v_mfma_f32_16x16x32_bf16 v[186:189], v[190:193], v[96:99], 0
	v_mfma_f32_16x16x32_bf16 v[186:189], v[194:197], v[100:103], v[186:189]
	s_setprio 0
	s_nop 6
	v_cndmask_b32_e64 v162, v186, v182, s[2:3]
	v_add_f32_e32 v136, v136, v162
	v_exp_f32_e32 v162, v136
	v_cndmask_b32_e64 v136, v187, v183, s[4:5]
	v_cndmask_b32_e64 v183, v184, v188, s[22:23]
	s_waitcnt lgkmcnt(15)
	v_add_f32_e32 v165, v165, v183
	v_exp_f32_e32 v190, v165
	v_cndmask_b32_e64 v165, v185, v189, s[24:25]
	v_add_f32_e32 v136, v223, v136
	s_waitcnt lgkmcnt(15)
	v_add_f32_e32 v165, v224, v165
	v_exp_f32_e32 v178, v136
	v_exp_f32_e32 v192, v165
	v_cndmask_b32_e64 v183, v190, 0, s[22:23]
	v_cndmask_b32_e64 v185, 0, v190, s[22:23]
	v_cndmask_b32_e64 v182, 0, v178, s[4:5]
	v_cndmask_b32_e64 v184, v192, 0, s[24:25]
	v_cndmask_b32_e64 v136, 0, v162, s[2:3]
	v_cndmask_b32_e64 v163, v162, 0, s[2:3]
	v_cndmask_b32_e64 v165, v178, 0, s[4:5]
	v_cndmask_b32_e64 v186, 0, v192, s[24:25]
	v_cvt_pk_bf16_f32 v182, v136, v182
	v_cvt_pk_bf16_f32 v183, v183, v184
	v_cvt_pk_bf16_f32 v184, v163, v165
	v_cvt_pk_bf16_f32 v185, v185, v186
	s_setprio 1
	s_waitcnt lgkmcnt(14)
	v_mfma_f32_16x16x32_bf16 v[28:31], v[158:161], v[182:185], v[28:31]
	s_waitcnt lgkmcnt(12)
	v_mfma_f32_16x16x32_bf16 v[24:27], v[166:169], v[182:185], v[24:27]
	s_waitcnt lgkmcnt(10)
	v_mfma_f32_16x16x32_bf16 v[20:23], v[170:173], v[182:185], v[20:23]
	s_waitcnt lgkmcnt(8)
	v_mfma_f32_16x16x32_bf16 v[16:19], v[174:177], v[182:185], v[16:19]
	s_setprio 0
	ds_read_b64 v[158:159], v220 offset:1088
	ds_read_b64 v[160:161], v220 offset:1120
	ds_read_b64 v[166:167], v219 offset:1600
	ds_read_b64 v[168:169], v219 offset:1632
	ds_read_b64 v[170:171], v218 offset:1344
	ds_read_b64 v[172:173], v218 offset:1376
	ds_read_b64 v[174:175], v181 offset:1088
	ds_read_b64 v[176:177], v181 offset:1120
	s_setprio 1
	s_waitcnt vmcnt(1) lgkmcnt(15)
	v_mfma_f32_16x16x32_bf16 v[182:185], v[198:201], v[104:107], 0
	s_waitcnt lgkmcnt(13)
	v_mfma_f32_16x16x32_bf16 v[186:189], v[206:209], v[104:107], 0
	s_waitcnt vmcnt(0)
	v_mfma_f32_16x16x32_bf16 v[182:185], v[202:205], v[108:111], v[182:185]
	s_waitcnt lgkmcnt(12)
	v_mfma_f32_16x16x32_bf16 v[186:189], v[210:213], v[108:111], v[186:189]
	s_setprio 0
	s_nop 6
	v_cndmask_b32_e64 v136, v182, v186, s[26:27]
	s_waitcnt lgkmcnt(11)
	v_add_f32_e32 v119, v119, v136
	v_exp_f32_e32 v163, v119
	v_cndmask_b32_e64 v119, v183, v187, s[28:29]
	v_cndmask_b32_e64 v181, v184, v188, s[30:31]
	s_waitcnt lgkmcnt(10)
	v_add_f32_e32 v119, v179, v119
	s_waitcnt lgkmcnt(9)
	v_add_f32_e32 v181, v214, v181
	v_exp_f32_e32 v179, v119
	v_exp_f32_e32 v191, v181
	v_cndmask_b32_e64 v181, v185, v189, s[34:35]
	s_waitcnt lgkmcnt(8)
	v_add_f32_e32 v181, v215, v181
	v_exp_f32_e32 v193, v181
	v_cndmask_b32_e64 v119, v163, 0, s[26:27]
	v_cndmask_b32_e64 v136, 0, v163, s[26:27]
	v_pk_add_f32 v[162:163], v[162:163], 0 op_sel_hi:[1,0]
	v_cndmask_b32_e64 v183, v191, 0, s[30:31]
	v_pk_add_f32 v[162:163], v[178:179], v[162:163]
	v_cndmask_b32_e64 v185, 0, v191, s[30:31]
	v_pk_add_f32 v[162:163], v[190:191], v[162:163]
	v_cndmask_b32_e64 v184, v193, 0, s[34:35]
	v_pk_add_f32 v[162:163], v[192:193], v[162:163]
	v_cndmask_b32_e64 v165, v179, 0, s[28:29]
	v_pk_add_f32 v[124:125], v[124:125], v[162:163]
	v_cndmask_b32_e64 v181, 0, v179, s[28:29]
	v_cndmask_b32_e64 v186, 0, v193, s[34:35]
	v_cvt_pk_bf16_f32 v182, v119, v165
	v_cvt_pk_bf16_f32 v183, v183, v184
	v_cvt_pk_bf16_f32 v184, v136, v181
	v_cvt_pk_bf16_f32 v185, v185, v186
	s_setprio 1
	s_waitcnt lgkmcnt(0)
	v_mfma_f32_16x16x32_bf16 v[12:15], v[174:177], v[182:185], v[12:15]
	v_mfma_f32_16x16x32_bf16 v[8:11], v[170:173], v[182:185], v[8:11]
	v_mfma_f32_16x16x32_bf16 v[4:7], v[166:169], v[182:185], v[4:7]
	v_mfma_f32_16x16x32_bf16 v[0:3], v[158:161], v[182:185], v[0:3]
	s_setprio 0

.LBB0_590:
	s_add_i32 s70, s52, -3
	s_cmp_ge_u32 s70, s38
	s_cselect_b64 s[66:67], -1, 0
	s_cmp_lt_u32 s70, s39
	s_cselect_b64 s[72:73], -1, 0
	s_and_b64 s[66:67], s[66:67], s[72:73]
	s_andn2_b64 vcc, exec, s[66:67]
	s_cbranch_vccnz .LBB0_592
	v_add_u32_e32 v178, v150, v149
	v_add_u32_e32 v181, 0x2000, v178
	v_add_u32_e32 v218, 0x2800, v178
	v_add_u32_e32 v219, 0x3000, v178
	v_add_u32_e32 v178, v150, v151
	v_add_u32_e32 v119, v148, v149
	v_add_u32_e32 v136, s68, v152
	v_add_u32_sdwa v163, s68, v144 dst_sel:DWORD dst_unused:UNUSED_PAD src0_sel:DWORD src1_sel:BYTE_2
	v_add_u32_sdwa v165, s68, v144 dst_sel:DWORD dst_unused:UNUSED_PAD src0_sel:DWORD src1_sel:BYTE_3
	v_add_u32_e32 v220, 0x2000, v178
	v_add_u32_sdwa v179, s68, v142 dst_sel:DWORD dst_unused:UNUSED_PAD src0_sel:DWORD src1_sel:BYTE_1
	ds_read_b128 v[158:161], v119
	ds_read_b128 v[166:169], v119 offset:64
	ds_read_b128 v[170:173], v119 offset:2304
	ds_read_b128 v[174:177], v119 offset:2368
	v_add_u32_e32 v162, s68, v153
	ds_read_b64 v[182:183], v181 offset:1024
	ds_read_b64 v[184:185], v181 offset:1056
	ds_read_b64 v[186:187], v218 offset:1280
	ds_read_b64 v[188:189], v218 offset:1312
	ds_read_b64 v[190:191], v219 offset:1536
	ds_read_b64 v[192:193], v219 offset:1568
	ds_read_b64 v[194:195], v220 offset:1024
	ds_read_b64 v[196:197], v220 offset:1056
	ds_read_b128 v[198:201], v119 offset:1152
	ds_read_b128 v[202:205], v119 offset:1216
	ds_read_b128 v[206:209], v119 offset:3456
	ds_read_b128 v[210:213], v119 offset:3520
	v_add_u32_e32 v178, s68, v155
	v_add_u32_sdwa v214, s68, v143 dst_sel:DWORD dst_unused:UNUSED_PAD src0_sel:DWORD src1_sel:BYTE_2
	v_add_u32_sdwa v215, s68, v143 dst_sel:DWORD dst_unused:UNUSED_PAD src0_sel:DWORD src1_sel:BYTE_3
	ds_read_b32 v136, v136 offset:41856
	ds_read_b32 v216, v162 offset:41856
	ds_read_b32 v163, v163 offset:41856
	ds_read_b32 v165, v165 offset:41856
	ds_read_b32 v217, v178 offset:41856
	ds_read_b32 v179, v179 offset:41856
	ds_read_b32 v221, v214 offset:41856
	ds_read_b32 v222, v215 offset:41856
	s_setprio 1
	s_waitcnt vmcnt(7) lgkmcnt(15)
	v_mfma_f32_16x16x32_bf16 v[158:161], v[158:161], v[80:83], 0
	s_waitcnt vmcnt(6)
	v_mfma_f32_16x16x32_bf16 v[158:161], v[166:169], v[84:87], v[158:161]
	v_mfma_f32_16x16x32_bf16 v[166:169], v[170:173], v[80:83], 0
	v_mfma_f32_16x16x32_bf16 v[166:169], v[174:177], v[84:87], v[166:169]
	s_setprio 0
	s_nop 6
	v_cndmask_b32_e64 v158, v166, v158, s[20:21]
	s_waitcnt lgkmcnt(7)
	v_add_f32_e32 v136, v136, v158
	v_exp_f32_e32 v162, v136
	v_cndmask_b32_e64 v136, v159, v167, s[10:11]
	v_cndmask_b32_e64 v159, v160, v168, s[12:13]
	s_waitcnt lgkmcnt(5)
	v_add_f32_e32 v159, v163, v159
	v_add_f32_e32 v136, v216, v136
	v_exp_f32_e32 v214, v159
	v_cndmask_b32_e64 v159, v161, v169, s[14:15]
	v_exp_f32_e32 v178, v136
	s_waitcnt lgkmcnt(4)
	v_add_f32_e32 v159, v165, v159
	v_exp_f32_e32 v216, v159
	v_cndmask_b32_e64 v159, v214, 0, s[12:13]
	v_cndmask_b32_e64 v158, v178, 0, s[10:11]
	v_cndmask_b32_e64 v160, 0, v178, s[10:11]
	v_cndmask_b32_e64 v161, 0, v214, s[12:13]
	v_cndmask_b32_e64 v136, 0, v162, s[20:21]
	v_cndmask_b32_e64 v166, v162, 0, s[20:21]
	v_cndmask_b32_e64 v163, v216, 0, s[14:15]
	v_cndmask_b32_e64 v165, 0, v216, s[14:15]
	v_cvt_pk_bf16_f32 v158, v136, v158
	v_cvt_pk_bf16_f32 v159, v159, v163
	v_cvt_pk_bf16_f32 v160, v166, v160
	v_cvt_pk_bf16_f32 v161, v161, v165
	s_setprio 1
	v_mfma_f32_16x16x32_bf16 v[60:63], v[182:185], v[158:161], v[60:63]
	v_mfma_f32_16x16x32_bf16 v[56:59], v[186:189], v[158:161], v[56:59]
	v_mfma_f32_16x16x32_bf16 v[52:55], v[190:193], v[158:161], v[52:55]
	v_mfma_f32_16x16x32_bf16 v[48:51], v[194:197], v[158:161], v[48:51]
	s_setprio 0
	ds_read_b64 v[158:159], v181 offset:1040
	ds_read_b64 v[160:161], v181 offset:1072
	ds_read_b64 v[166:167], v218 offset:1296
	ds_read_b64 v[168:169], v218 offset:1328
	ds_read_b64 v[170:171], v219 offset:1552
	ds_read_b64 v[172:173], v219 offset:1584
	ds_read_b64 v[174:175], v220 offset:1040
	ds_read_b64 v[176:177], v220 offset:1072
	ds_read_b128 v[182:185], v119 offset:3456
	ds_read_b128 v[186:189], v119 offset:3520
	ds_read_b128 v[190:193], v119 offset:5760
	ds_read_b128 v[194:197], v119 offset:5824
	v_add_u32_e32 v136, s68, v156
	v_add_u32_sdwa v165, s68, v141 dst_sel:DWORD dst_unused:UNUSED_PAD src0_sel:DWORD src1_sel:BYTE_2
	v_add_u32_sdwa v163, s68, v140 dst_sel:DWORD dst_unused:UNUSED_PAD src0_sel:DWORD src1_sel:BYTE_1
	v_add_u32_sdwa v215, s68, v141 dst_sel:DWORD dst_unused:UNUSED_PAD src0_sel:DWORD src1_sel:BYTE_3
	ds_read_b32 v136, v136 offset:41856
	ds_read_b32 v223, v163 offset:41856
	ds_read_b32 v165, v165 offset:41856
	ds_read_b32 v224, v215 offset:41856
	s_setprio 1
	s_waitcnt vmcnt(5)
	v_mfma_f32_16x16x32_bf16 v[198:201], v[198:201], v[88:91], 0
	s_waitcnt vmcnt(4)
	v_mfma_f32_16x16x32_bf16 v[198:201], v[202:205], v[92:95], v[198:201]
	v_mfma_f32_16x16x32_bf16 v[202:205], v[206:209], v[88:91], 0
	v_mfma_f32_16x16x32_bf16 v[202:205], v[210:213], v[92:95], v[202:205]
	s_setprio 0
	s_nop 6
	v_cndmask_b32_e64 v163, v198, v202, s[16:17]
	s_waitcnt lgkmcnt(15)
	v_add_f32_e32 v163, v217, v163
	v_cndmask_b32_e64 v198, v199, v203, s[18:19]
	v_cndmask_b32_e64 v200, v200, v204, s[6:7]
	v_exp_f32_e32 v163, v163
	v_add_f32_e32 v179, v179, v198
	s_waitcnt lgkmcnt(15)
	v_add_f32_e32 v200, v221, v200
	v_exp_f32_e32 v179, v179
	v_exp_f32_e32 v215, v200
	v_cndmask_b32_e64 v200, v201, v205, s[8:9]
	s_waitcnt lgkmcnt(15)
	v_add_f32_e32 v200, v222, v200
	v_exp_f32_e32 v217, v200
	v_cndmask_b32_e64 v198, v163, 0, s[16:17]
	v_cndmask_b32_e64 v202, 0, v163, s[16:17]
	v_pk_add_f32 v[162:163], v[162:163], 0 op_sel_hi:[1,0]
	v_cndmask_b32_e64 v199, v179, 0, s[18:19]
	v_pk_add_f32 v[162:163], v[178:179], v[162:163]
	v_cndmask_b32_e64 v200, 0, v179, s[18:19]
	v_pk_add_f32 v[162:163], v[214:215], v[162:163]
	v_cndmask_b32_e64 v201, v215, 0, s[6:7]
	v_pk_add_f32 v[162:163], v[216:217], v[162:163]
	v_cndmask_b32_e64 v203, 0, v215, s[6:7]
	v_pk_add_f32 v[130:131], v[130:131], v[162:163]
	v_cndmask_b32_e64 v204, v217, 0, s[8:9]
	v_cndmask_b32_e64 v205, 0, v217, s[8:9]
	v_cvt_pk_bf16_f32 v198, v198, v199
	v_cvt_pk_bf16_f32 v199, v201, v204
	v_cvt_pk_bf16_f32 v200, v202, v200
	v_cvt_pk_bf16_f32 v201, v203, v205
	s_setprio 1
	s_waitcnt lgkmcnt(14)
	v_mfma_f32_16x16x32_bf16 v[44:47], v[158:161], v[198:201], v[44:47]
	s_waitcnt lgkmcnt(12)
	v_mfma_f32_16x16x32_bf16 v[40:43], v[166:169], v[198:201], v[40:43]
	s_waitcnt lgkmcnt(10)
	v_mfma_f32_16x16x32_bf16 v[36:39], v[170:173], v[198:201], v[36:39]
	s_waitcnt lgkmcnt(8)
	v_mfma_f32_16x16x32_bf16 v[32:35], v[174:177], v[198:201], v[32:35]
	s_setprio 0
	ds_read_b64 v[158:159], v181 offset:1072
	ds_read_b64 v[160:161], v181 offset:1104
	ds_read_b64 v[166:167], v218 offset:1328
	ds_read_b64 v[168:169], v218 offset:1360
	ds_read_b64 v[170:171], v219 offset:1584
	ds_read_b64 v[172:173], v219 offset:1616
	ds_read_b64 v[174:175], v220 offset:1072
	ds_read_b64 v[176:177], v220 offset:1104
	ds_read_b128 v[198:201], v119 offset:4608
	ds_read_b128 v[202:205], v119 offset:4672
	v_add_u32_e32 v119, v148, v151
	ds_read_b128 v[206:209], v119
	ds_read_b128 v[210:213], v119 offset:64
	v_add_u32_e32 v119, s68, v154
	v_add_u32_sdwa v162, s68, v145 dst_sel:DWORD dst_unused:UNUSED_PAD src0_sel:DWORD src1_sel:BYTE_1
	v_add_u32_sdwa v163, s68, v146 dst_sel:DWORD dst_unused:UNUSED_PAD src0_sel:DWORD src1_sel:BYTE_2
	v_add_u32_sdwa v178, s68, v146 dst_sel:DWORD dst_unused:UNUSED_PAD src0_sel:DWORD src1_sel:BYTE_3
	ds_read_b32 v119, v119 offset:41856
	ds_read_b32 v179, v162 offset:41856
	ds_read_b32 v214, v163 offset:41856
	ds_read_b32 v215, v178 offset:41856
	s_setprio 1
	s_waitcnt vmcnt(3) lgkmcnt(15)
	v_mfma_f32_16x16x32_bf16 v[182:185], v[182:185], v[96:99], 0
	s_waitcnt vmcnt(2)
	v_mfma_f32_16x16x32_bf16 v[182:185], v[186:189], v[100:103], v[182:185]
	v_mfma_f32_16x16x32_bf16 v[186:189], v[190:193], v[96:99], 0
	v_mfma_f32_16x16x32_bf16 v[186:189], v[194:197], v[100:103], v[186:189]
	s_setprio 0
	s_nop 6
	v_cndmask_b32_e64 v162, v186, v182, s[2:3]
	v_add_f32_e32 v136, v136, v162
	v_exp_f32_e32 v162, v136
	v_cndmask_b32_e64 v136, v187, v183, s[4:5]
	v_cndmask_b32_e64 v183, v184, v188, s[22:23]
	s_waitcnt lgkmcnt(15)
	v_add_f32_e32 v165, v165, v183
	v_exp_f32_e32 v190, v165
	v_cndmask_b32_e64 v165, v185, v189, s[24:25]
	v_add_f32_e32 v136, v223, v136
	s_waitcnt lgkmcnt(15)
	v_add_f32_e32 v165, v224, v165
	v_exp_f32_e32 v178, v136
	v_exp_f32_e32 v192, v165
	v_cndmask_b32_e64 v183, v190, 0, s[22:23]
	v_cndmask_b32_e64 v185, 0, v190, s[22:23]
	v_cndmask_b32_e64 v182, 0, v178, s[4:5]
	v_cndmask_b32_e64 v184, v192, 0, s[24:25]
	v_cndmask_b32_e64 v136, 0, v162, s[2:3]
	v_cndmask_b32_e64 v163, v162, 0, s[2:3]
	v_cndmask_b32_e64 v165, v178, 0, s[4:5]
	v_cndmask_b32_e64 v186, 0, v192, s[24:25]
	v_cvt_pk_bf16_f32 v182, v136, v182
	v_cvt_pk_bf16_f32 v183, v183, v184
	v_cvt_pk_bf16_f32 v184, v163, v165
	v_cvt_pk_bf16_f32 v185, v185, v186
	s_setprio 1
	s_waitcnt lgkmcnt(14)
	v_mfma_f32_16x16x32_bf16 v[28:31], v[158:161], v[182:185], v[28:31]
	s_waitcnt lgkmcnt(12)
	v_mfma_f32_16x16x32_bf16 v[24:27], v[166:169], v[182:185], v[24:27]
	s_waitcnt lgkmcnt(10)
	v_mfma_f32_16x16x32_bf16 v[20:23], v[170:173], v[182:185], v[20:23]
	s_waitcnt lgkmcnt(8)
	v_mfma_f32_16x16x32_bf16 v[16:19], v[174:177], v[182:185], v[16:19]
	s_setprio 0
	ds_read_b64 v[158:159], v220 offset:1088
	ds_read_b64 v[160:161], v220 offset:1120
	ds_read_b64 v[166:167], v219 offset:1600
	ds_read_b64 v[168:169], v219 offset:1632
	ds_read_b64 v[170:171], v218 offset:1344
	ds_read_b64 v[172:173], v218 offset:1376
	ds_read_b64 v[174:175], v181 offset:1088
	ds_read_b64 v[176:177], v181 offset:1120
	s_setprio 1
	s_waitcnt vmcnt(1) lgkmcnt(15)
	v_mfma_f32_16x16x32_bf16 v[182:185], v[198:201], v[104:107], 0
	s_waitcnt lgkmcnt(13)
	v_mfma_f32_16x16x32_bf16 v[186:189], v[206:209], v[104:107], 0
	s_waitcnt vmcnt(0)
	v_mfma_f32_16x16x32_bf16 v[182:185], v[202:205], v[108:111], v[182:185]
	s_waitcnt lgkmcnt(12)
	v_mfma_f32_16x16x32_bf16 v[186:189], v[210:213], v[108:111], v[186:189]
	s_setprio 0
	s_nop 6
	v_cndmask_b32_e64 v136, v182, v186, s[26:27]
	s_waitcnt lgkmcnt(11)
	v_add_f32_e32 v119, v119, v136
	v_exp_f32_e32 v163, v119
	v_cndmask_b32_e64 v119, v183, v187, s[28:29]
	v_cndmask_b32_e64 v181, v184, v188, s[30:31]
	s_waitcnt lgkmcnt(10)
	v_add_f32_e32 v119, v179, v119
	s_waitcnt lgkmcnt(9)
	v_add_f32_e32 v181, v214, v181
	v_exp_f32_e32 v179, v119
	v_exp_f32_e32 v191, v181
	v_cndmask_b32_e64 v181, v185, v189, s[34:35]
	s_waitcnt lgkmcnt(8)
	v_add_f32_e32 v181, v215, v181
	v_exp_f32_e32 v193, v181
	v_cndmask_b32_e64 v119, v163, 0, s[26:27]
	v_cndmask_b32_e64 v136, 0, v163, s[26:27]
	v_pk_add_f32 v[162:163], v[162:163], 0 op_sel_hi:[1,0]
	v_cndmask_b32_e64 v183, v191, 0, s[30:31]
	v_pk_add_f32 v[162:163], v[178:179], v[162:163]
	v_cndmask_b32_e64 v185, 0, v191, s[30:31]
	v_pk_add_f32 v[162:163], v[190:191], v[162:163]
	v_cndmask_b32_e64 v184, v193, 0, s[34:35]
	v_pk_add_f32 v[162:163], v[192:193], v[162:163]
	v_cndmask_b32_e64 v165, v179, 0, s[28:29]
	v_pk_add_f32 v[124:125], v[124:125], v[162:163]
	v_cndmask_b32_e64 v181, 0, v179, s[28:29]
	v_cndmask_b32_e64 v186, 0, v193, s[34:35]
	v_cvt_pk_bf16_f32 v182, v119, v165
	v_cvt_pk_bf16_f32 v183, v183, v184
	v_cvt_pk_bf16_f32 v184, v136, v181
	v_cvt_pk_bf16_f32 v185, v185, v186
	s_setprio 1
	s_waitcnt lgkmcnt(0)
	v_mfma_f32_16x16x32_bf16 v[12:15], v[174:177], v[182:185], v[12:15]
	v_mfma_f32_16x16x32_bf16 v[8:11], v[170:173], v[182:185], v[8:11]
	v_mfma_f32_16x16x32_bf16 v[4:7], v[166:169], v[182:185], v[4:7]
	v_mfma_f32_16x16x32_bf16 v[0:3], v[158:161], v[182:185], v[0:3]
	s_setprio 0

.LBB0_597:
	s_add_i32 s66, s52, -2
	s_cmp_ge_u32 s66, s38
	s_cselect_b64 s[70:71], -1, 0
	s_cmp_lt_u32 s66, s39
	s_cselect_b64 s[72:73], -1, 0
	s_and_b64 s[70:71], s[70:71], s[72:73]
	s_andn2_b64 vcc, exec, s[70:71]
	s_cbranch_vccnz .LBB0_599
	v_add_u32_e32 v178, v150, v149
	v_add_u32_e32 v181, 0x6800, v178
	v_add_u32_e32 v218, 0x7000, v178
	v_add_u32_e32 v219, 0x7800, v178
	v_add_u32_e32 v178, v150, v151
	v_add_u32_e32 v119, v148, v149
	v_add_u32_e32 v136, s68, v152
	v_add_u32_sdwa v163, s68, v144 dst_sel:DWORD dst_unused:UNUSED_PAD src0_sel:DWORD src1_sel:BYTE_2
	v_add_u32_sdwa v165, s68, v144 dst_sel:DWORD dst_unused:UNUSED_PAD src0_sel:DWORD src1_sel:BYTE_3
	v_add_u32_e32 v220, 0x6800, v178
	v_add_u32_sdwa v179, s68, v142 dst_sel:DWORD dst_unused:UNUSED_PAD src0_sel:DWORD src1_sel:BYTE_1
	ds_read_b128 v[158:161], v119 offset:18432
	ds_read_b128 v[166:169], v119 offset:18496
	ds_read_b128 v[170:173], v119 offset:20736
	ds_read_b128 v[174:177], v119 offset:20800
	v_add_u32_e32 v162, s68, v153
	ds_read_b64 v[182:183], v181 offset:1024
	ds_read_b64 v[184:185], v181 offset:1056
	ds_read_b64 v[186:187], v218 offset:1280
	ds_read_b64 v[188:189], v218 offset:1312
	ds_read_b64 v[190:191], v219 offset:1536
	ds_read_b64 v[192:193], v219 offset:1568
	ds_read_b64 v[194:195], v220 offset:1024
	ds_read_b64 v[196:197], v220 offset:1056
	ds_read_b128 v[198:201], v119 offset:19584
	ds_read_b128 v[202:205], v119 offset:19648
	ds_read_b128 v[206:209], v119 offset:21888
	ds_read_b128 v[210:213], v119 offset:21952
	v_add_u32_e32 v178, s68, v155
	v_add_u32_sdwa v214, s68, v143 dst_sel:DWORD dst_unused:UNUSED_PAD src0_sel:DWORD src1_sel:BYTE_2
	v_add_u32_sdwa v215, s68, v143 dst_sel:DWORD dst_unused:UNUSED_PAD src0_sel:DWORD src1_sel:BYTE_3
	ds_read_b32 v136, v136 offset:41984
	ds_read_b32 v216, v162 offset:41984
	ds_read_b32 v163, v163 offset:41984
	ds_read_b32 v165, v165 offset:41984
	ds_read_b32 v217, v178 offset:41984
	ds_read_b32 v179, v179 offset:41984
	ds_read_b32 v221, v214 offset:41984
	ds_read_b32 v222, v215 offset:41984
	s_setprio 1
	s_waitcnt vmcnt(7) lgkmcnt(15)
	v_mfma_f32_16x16x32_bf16 v[158:161], v[158:161], v[80:83], 0
	s_waitcnt vmcnt(6)
	v_mfma_f32_16x16x32_bf16 v[158:161], v[166:169], v[84:87], v[158:161]
	v_mfma_f32_16x16x32_bf16 v[166:169], v[170:173], v[80:83], 0
	v_mfma_f32_16x16x32_bf16 v[166:169], v[174:177], v[84:87], v[166:169]
	s_setprio 0
	s_nop 6
	v_cndmask_b32_e64 v158, v166, v158, s[20:21]
	s_waitcnt lgkmcnt(7)
	v_add_f32_e32 v136, v136, v158
	v_exp_f32_e32 v162, v136
	v_cndmask_b32_e64 v136, v159, v167, s[10:11]
	v_cndmask_b32_e64 v159, v160, v168, s[12:13]
	s_waitcnt lgkmcnt(5)
	v_add_f32_e32 v159, v163, v159
	v_add_f32_e32 v136, v216, v136
	v_exp_f32_e32 v214, v159
	v_cndmask_b32_e64 v159, v161, v169, s[14:15]
	v_exp_f32_e32 v178, v136
	s_waitcnt lgkmcnt(4)
	v_add_f32_e32 v159, v165, v159
	v_exp_f32_e32 v216, v159
	v_cndmask_b32_e64 v159, v214, 0, s[12:13]
	v_cndmask_b32_e64 v158, v178, 0, s[10:11]
	v_cndmask_b32_e64 v160, 0, v178, s[10:11]
	v_cndmask_b32_e64 v161, 0, v214, s[12:13]
	v_cndmask_b32_e64 v136, 0, v162, s[20:21]
	v_cndmask_b32_e64 v166, v162, 0, s[20:21]
	v_cndmask_b32_e64 v163, v216, 0, s[14:15]
	v_cndmask_b32_e64 v165, 0, v216, s[14:15]
	v_cvt_pk_bf16_f32 v158, v136, v158
	v_cvt_pk_bf16_f32 v159, v159, v163
	v_cvt_pk_bf16_f32 v160, v166, v160
	v_cvt_pk_bf16_f32 v161, v161, v165
	s_setprio 1
	v_mfma_f32_16x16x32_bf16 v[60:63], v[182:185], v[158:161], v[60:63]
	v_mfma_f32_16x16x32_bf16 v[56:59], v[186:189], v[158:161], v[56:59]
	v_mfma_f32_16x16x32_bf16 v[52:55], v[190:193], v[158:161], v[52:55]
	v_mfma_f32_16x16x32_bf16 v[48:51], v[194:197], v[158:161], v[48:51]
	s_setprio 0
	ds_read_b64 v[158:159], v181 offset:1040
	ds_read_b64 v[160:161], v181 offset:1072
	ds_read_b64 v[166:167], v218 offset:1296
	ds_read_b64 v[168:169], v218 offset:1328
	ds_read_b64 v[170:171], v219 offset:1552
	ds_read_b64 v[172:173], v219 offset:1584
	ds_read_b64 v[174:175], v220 offset:1040
	ds_read_b64 v[176:177], v220 offset:1072
	ds_read_b128 v[182:185], v119 offset:21888
	ds_read_b128 v[186:189], v119 offset:21952
	ds_read_b128 v[190:193], v119 offset:24192
	ds_read_b128 v[194:197], v119 offset:24256
	v_add_u32_e32 v136, s68, v156
	v_add_u32_sdwa v165, s68, v141 dst_sel:DWORD dst_unused:UNUSED_PAD src0_sel:DWORD src1_sel:BYTE_2
	v_add_u32_sdwa v163, s68, v140 dst_sel:DWORD dst_unused:UNUSED_PAD src0_sel:DWORD src1_sel:BYTE_1
	v_add_u32_sdwa v215, s68, v141 dst_sel:DWORD dst_unused:UNUSED_PAD src0_sel:DWORD src1_sel:BYTE_3
	ds_read_b32 v136, v136 offset:41984
	ds_read_b32 v223, v163 offset:41984
	ds_read_b32 v165, v165 offset:41984
	ds_read_b32 v224, v215 offset:41984
	s_setprio 1
	s_waitcnt vmcnt(5)
	v_mfma_f32_16x16x32_bf16 v[198:201], v[198:201], v[88:91], 0
	s_waitcnt vmcnt(4)
	v_mfma_f32_16x16x32_bf16 v[198:201], v[202:205], v[92:95], v[198:201]
	v_mfma_f32_16x16x32_bf16 v[202:205], v[206:209], v[88:91], 0
	v_mfma_f32_16x16x32_bf16 v[202:205], v[210:213], v[92:95], v[202:205]
	s_setprio 0
	s_nop 6
	v_cndmask_b32_e64 v163, v198, v202, s[16:17]
	s_waitcnt lgkmcnt(15)
	v_add_f32_e32 v163, v217, v163
	v_cndmask_b32_e64 v198, v199, v203, s[18:19]
	v_cndmask_b32_e64 v200, v200, v204, s[6:7]
	v_exp_f32_e32 v163, v163
	v_add_f32_e32 v179, v179, v198
	s_waitcnt lgkmcnt(15)
	v_add_f32_e32 v200, v221, v200
	v_exp_f32_e32 v179, v179
	v_exp_f32_e32 v215, v200
	v_cndmask_b32_e64 v200, v201, v205, s[8:9]
	s_waitcnt lgkmcnt(15)
	v_add_f32_e32 v200, v222, v200
	v_exp_f32_e32 v217, v200
	v_cndmask_b32_e64 v198, v163, 0, s[16:17]
	v_cndmask_b32_e64 v202, 0, v163, s[16:17]
	v_pk_add_f32 v[162:163], v[162:163], 0 op_sel_hi:[1,0]
	v_cndmask_b32_e64 v199, v179, 0, s[18:19]
	v_pk_add_f32 v[162:163], v[178:179], v[162:163]
	v_cndmask_b32_e64 v200, 0, v179, s[18:19]
	v_pk_add_f32 v[162:163], v[214:215], v[162:163]
	v_cndmask_b32_e64 v201, v215, 0, s[6:7]
	v_pk_add_f32 v[162:163], v[216:217], v[162:163]
	v_cndmask_b32_e64 v203, 0, v215, s[6:7]
	v_pk_add_f32 v[130:131], v[130:131], v[162:163]
	v_cndmask_b32_e64 v204, v217, 0, s[8:9]
	v_cndmask_b32_e64 v205, 0, v217, s[8:9]
	v_cvt_pk_bf16_f32 v198, v198, v199
	v_cvt_pk_bf16_f32 v199, v201, v204
	v_cvt_pk_bf16_f32 v200, v202, v200
	v_cvt_pk_bf16_f32 v201, v203, v205
	s_setprio 1
	s_waitcnt lgkmcnt(14)
	v_mfma_f32_16x16x32_bf16 v[44:47], v[158:161], v[198:201], v[44:47]
	s_waitcnt lgkmcnt(12)
	v_mfma_f32_16x16x32_bf16 v[40:43], v[166:169], v[198:201], v[40:43]
	s_waitcnt lgkmcnt(10)
	v_mfma_f32_16x16x32_bf16 v[36:39], v[170:173], v[198:201], v[36:39]
	s_waitcnt lgkmcnt(8)
	v_mfma_f32_16x16x32_bf16 v[32:35], v[174:177], v[198:201], v[32:35]
	s_setprio 0
	ds_read_b64 v[158:159], v181 offset:1072
	ds_read_b64 v[160:161], v181 offset:1104
	ds_read_b64 v[166:167], v218 offset:1328
	ds_read_b64 v[168:169], v218 offset:1360
	ds_read_b64 v[170:171], v219 offset:1584
	ds_read_b64 v[172:173], v219 offset:1616
	ds_read_b64 v[174:175], v220 offset:1072
	ds_read_b64 v[176:177], v220 offset:1104
	ds_read_b128 v[198:201], v119 offset:23040
	ds_read_b128 v[202:205], v119 offset:23104
	v_add_u32_e32 v119, v148, v151
	ds_read_b128 v[206:209], v119 offset:18432
	ds_read_b128 v[210:213], v119 offset:18496
	v_add_u32_e32 v119, s68, v154
	v_add_u32_sdwa v162, s68, v145 dst_sel:DWORD dst_unused:UNUSED_PAD src0_sel:DWORD src1_sel:BYTE_1
	v_add_u32_sdwa v163, s68, v146 dst_sel:DWORD dst_unused:UNUSED_PAD src0_sel:DWORD src1_sel:BYTE_2
	v_add_u32_sdwa v178, s68, v146 dst_sel:DWORD dst_unused:UNUSED_PAD src0_sel:DWORD src1_sel:BYTE_3
	ds_read_b32 v119, v119 offset:41984
	ds_read_b32 v179, v162 offset:41984
	ds_read_b32 v214, v163 offset:41984
	ds_read_b32 v215, v178 offset:41984
	s_setprio 1
	s_waitcnt vmcnt(3) lgkmcnt(15)
	v_mfma_f32_16x16x32_bf16 v[182:185], v[182:185], v[96:99], 0
	s_waitcnt vmcnt(2)
	v_mfma_f32_16x16x32_bf16 v[182:185], v[186:189], v[100:103], v[182:185]
	v_mfma_f32_16x16x32_bf16 v[186:189], v[190:193], v[96:99], 0
	v_mfma_f32_16x16x32_bf16 v[186:189], v[194:197], v[100:103], v[186:189]
	s_setprio 0
	s_nop 6
	v_cndmask_b32_e64 v162, v186, v182, s[2:3]
	v_add_f32_e32 v136, v136, v162
	v_exp_f32_e32 v162, v136
	v_cndmask_b32_e64 v136, v187, v183, s[4:5]
	v_cndmask_b32_e64 v183, v184, v188, s[22:23]
	s_waitcnt lgkmcnt(15)
	v_add_f32_e32 v165, v165, v183
	v_exp_f32_e32 v190, v165
	v_cndmask_b32_e64 v165, v185, v189, s[24:25]
	v_add_f32_e32 v136, v223, v136
	s_waitcnt lgkmcnt(15)
	v_add_f32_e32 v165, v224, v165
	v_exp_f32_e32 v178, v136
	v_exp_f32_e32 v192, v165
	v_cndmask_b32_e64 v183, v190, 0, s[22:23]
	v_cndmask_b32_e64 v185, 0, v190, s[22:23]
	v_cndmask_b32_e64 v182, 0, v178, s[4:5]
	v_cndmask_b32_e64 v184, v192, 0, s[24:25]
	v_cndmask_b32_e64 v136, 0, v162, s[2:3]
	v_cndmask_b32_e64 v163, v162, 0, s[2:3]
	v_cndmask_b32_e64 v165, v178, 0, s[4:5]
	v_cndmask_b32_e64 v186, 0, v192, s[24:25]
	v_cvt_pk_bf16_f32 v182, v136, v182
	v_cvt_pk_bf16_f32 v183, v183, v184
	v_cvt_pk_bf16_f32 v184, v163, v165
	v_cvt_pk_bf16_f32 v185, v185, v186
	s_setprio 1
	s_waitcnt lgkmcnt(14)
	v_mfma_f32_16x16x32_bf16 v[28:31], v[158:161], v[182:185], v[28:31]
	s_waitcnt lgkmcnt(12)
	v_mfma_f32_16x16x32_bf16 v[24:27], v[166:169], v[182:185], v[24:27]
	s_waitcnt lgkmcnt(10)
	v_mfma_f32_16x16x32_bf16 v[20:23], v[170:173], v[182:185], v[20:23]
	s_waitcnt lgkmcnt(8)
	v_mfma_f32_16x16x32_bf16 v[16:19], v[174:177], v[182:185], v[16:19]
	s_setprio 0
	ds_read_b64 v[158:159], v220 offset:1088
	ds_read_b64 v[160:161], v220 offset:1120
	ds_read_b64 v[166:167], v219 offset:1600
	ds_read_b64 v[168:169], v219 offset:1632
	ds_read_b64 v[170:171], v218 offset:1344
	ds_read_b64 v[172:173], v218 offset:1376
	ds_read_b64 v[174:175], v181 offset:1088
	ds_read_b64 v[176:177], v181 offset:1120
	s_setprio 1
	s_waitcnt vmcnt(1) lgkmcnt(15)
	v_mfma_f32_16x16x32_bf16 v[182:185], v[198:201], v[104:107], 0
	s_waitcnt lgkmcnt(13)
	v_mfma_f32_16x16x32_bf16 v[186:189], v[206:209], v[104:107], 0
	s_waitcnt vmcnt(0)
	v_mfma_f32_16x16x32_bf16 v[182:185], v[202:205], v[108:111], v[182:185]
	s_waitcnt lgkmcnt(12)
	v_mfma_f32_16x16x32_bf16 v[186:189], v[210:213], v[108:111], v[186:189]
	s_setprio 0
	s_nop 6
	v_cndmask_b32_e64 v136, v182, v186, s[26:27]
	s_waitcnt lgkmcnt(11)
	v_add_f32_e32 v119, v119, v136
	v_exp_f32_e32 v163, v119
	v_cndmask_b32_e64 v119, v183, v187, s[28:29]
	v_cndmask_b32_e64 v181, v184, v188, s[30:31]
	s_waitcnt lgkmcnt(10)
	v_add_f32_e32 v119, v179, v119
	s_waitcnt lgkmcnt(9)
	v_add_f32_e32 v181, v214, v181
	v_exp_f32_e32 v179, v119
	v_exp_f32_e32 v191, v181
	v_cndmask_b32_e64 v181, v185, v189, s[34:35]
	s_waitcnt lgkmcnt(8)
	v_add_f32_e32 v181, v215, v181
	v_exp_f32_e32 v193, v181
	v_cndmask_b32_e64 v119, v163, 0, s[26:27]
	v_cndmask_b32_e64 v136, 0, v163, s[26:27]
	v_pk_add_f32 v[162:163], v[162:163], 0 op_sel_hi:[1,0]
	v_cndmask_b32_e64 v183, v191, 0, s[30:31]
	v_pk_add_f32 v[162:163], v[178:179], v[162:163]
	v_cndmask_b32_e64 v185, 0, v191, s[30:31]
	v_pk_add_f32 v[162:163], v[190:191], v[162:163]
	v_cndmask_b32_e64 v184, v193, 0, s[34:35]
	v_pk_add_f32 v[162:163], v[192:193], v[162:163]
	v_cndmask_b32_e64 v165, v179, 0, s[28:29]
	v_pk_add_f32 v[124:125], v[124:125], v[162:163]
	v_cndmask_b32_e64 v181, 0, v179, s[28:29]
	v_cndmask_b32_e64 v186, 0, v193, s[34:35]
	v_cvt_pk_bf16_f32 v182, v119, v165
	v_cvt_pk_bf16_f32 v183, v183, v184
	v_cvt_pk_bf16_f32 v184, v136, v181
	v_cvt_pk_bf16_f32 v185, v185, v186
	s_setprio 1
	s_waitcnt lgkmcnt(0)
	v_mfma_f32_16x16x32_bf16 v[12:15], v[174:177], v[182:185], v[12:15]
	v_mfma_f32_16x16x32_bf16 v[8:11], v[170:173], v[182:185], v[8:11]
	v_mfma_f32_16x16x32_bf16 v[4:7], v[166:169], v[182:185], v[4:7]
	v_mfma_f32_16x16x32_bf16 v[0:3], v[158:161], v[182:185], v[0:3]
	s_setprio 0

.LBB0_690:
	s_add_i32 s62, s40, -3
	s_cmp_ge_u32 s62, s38
	s_cselect_b64 s[52:53], -1, 0
	s_cmp_lt_u32 s62, s39
	s_cselect_b64 s[74:75], -1, 0
	s_and_b64 s[52:53], s[52:53], s[74:75]
	s_andn2_b64 vcc, exec, s[52:53]
	s_cbranch_vccnz .LBB0_692
	v_add_u32_e32 v178, v150, v149
	v_add_u32_e32 v181, 0x2000, v178
	v_add_u32_e32 v218, 0x2800, v178
	v_add_u32_e32 v219, 0x3000, v178
	v_add_u32_e32 v178, v150, v151
	v_add_u32_e32 v119, v148, v149
	v_add_u32_e32 v136, s60, v152
	v_add_u32_sdwa v163, s60, v144 dst_sel:DWORD dst_unused:UNUSED_PAD src0_sel:DWORD src1_sel:BYTE_2
	v_add_u32_sdwa v165, s60, v144 dst_sel:DWORD dst_unused:UNUSED_PAD src0_sel:DWORD src1_sel:BYTE_3
	v_add_u32_e32 v220, 0x2000, v178
	v_add_u32_sdwa v179, s60, v142 dst_sel:DWORD dst_unused:UNUSED_PAD src0_sel:DWORD src1_sel:BYTE_1
	ds_read_b128 v[158:161], v119
	ds_read_b128 v[166:169], v119 offset:64
	ds_read_b128 v[170:173], v119 offset:2304
	ds_read_b128 v[174:177], v119 offset:2368
	v_add_u32_e32 v162, s60, v153
	ds_read_b64 v[182:183], v181 offset:1024
	ds_read_b64 v[184:185], v181 offset:1056
	ds_read_b64 v[186:187], v218 offset:1280
	ds_read_b64 v[188:189], v218 offset:1312
	ds_read_b64 v[190:191], v219 offset:1536
	ds_read_b64 v[192:193], v219 offset:1568
	ds_read_b64 v[194:195], v220 offset:1024
	ds_read_b64 v[196:197], v220 offset:1056
	ds_read_b128 v[198:201], v119 offset:1152
	ds_read_b128 v[202:205], v119 offset:1216
	ds_read_b128 v[206:209], v119 offset:3456
	ds_read_b128 v[210:213], v119 offset:3520
	v_add_u32_e32 v178, s60, v155
	v_add_u32_sdwa v214, s60, v143 dst_sel:DWORD dst_unused:UNUSED_PAD src0_sel:DWORD src1_sel:BYTE_2
	v_add_u32_sdwa v215, s60, v143 dst_sel:DWORD dst_unused:UNUSED_PAD src0_sel:DWORD src1_sel:BYTE_3
	ds_read_b32 v136, v136 offset:41856
	ds_read_b32 v216, v162 offset:41856
	ds_read_b32 v163, v163 offset:41856
	ds_read_b32 v165, v165 offset:41856
	ds_read_b32 v217, v178 offset:41856
	ds_read_b32 v179, v179 offset:41856
	ds_read_b32 v221, v214 offset:41856
	ds_read_b32 v222, v215 offset:41856
	s_setprio 1
	s_waitcnt vmcnt(7) lgkmcnt(15)
	v_mfma_f32_16x16x32_bf16 v[158:161], v[158:161], v[80:83], 0
	s_waitcnt vmcnt(6)
	v_mfma_f32_16x16x32_bf16 v[158:161], v[166:169], v[84:87], v[158:161]
	v_mfma_f32_16x16x32_bf16 v[166:169], v[170:173], v[80:83], 0
	v_mfma_f32_16x16x32_bf16 v[166:169], v[174:177], v[84:87], v[166:169]
	s_setprio 0
	s_nop 6
	v_cndmask_b32_e64 v158, v166, v158, s[20:21]
	s_waitcnt lgkmcnt(7)
	v_add_f32_e32 v136, v136, v158
	v_exp_f32_e32 v162, v136
	v_cndmask_b32_e64 v136, v159, v167, s[10:11]
	v_cndmask_b32_e64 v159, v160, v168, s[12:13]
	s_waitcnt lgkmcnt(5)
	v_add_f32_e32 v159, v163, v159
	v_add_f32_e32 v136, v216, v136
	v_exp_f32_e32 v214, v159
	v_cndmask_b32_e64 v159, v161, v169, s[14:15]
	v_exp_f32_e32 v178, v136
	s_waitcnt lgkmcnt(4)
	v_add_f32_e32 v159, v165, v159
	v_exp_f32_e32 v216, v159
	v_cndmask_b32_e64 v159, v214, 0, s[12:13]
	v_cndmask_b32_e64 v158, v178, 0, s[10:11]
	v_cndmask_b32_e64 v160, 0, v178, s[10:11]
	v_cndmask_b32_e64 v161, 0, v214, s[12:13]
	v_cndmask_b32_e64 v136, 0, v162, s[20:21]
	v_cndmask_b32_e64 v166, v162, 0, s[20:21]
	v_cndmask_b32_e64 v163, v216, 0, s[14:15]
	v_cndmask_b32_e64 v165, 0, v216, s[14:15]
	v_cvt_pk_bf16_f32 v158, v136, v158
	v_cvt_pk_bf16_f32 v159, v159, v163
	v_cvt_pk_bf16_f32 v160, v166, v160
	v_cvt_pk_bf16_f32 v161, v161, v165
	s_setprio 1
	v_mfma_f32_16x16x32_bf16 v[60:63], v[182:185], v[158:161], v[60:63]
	v_mfma_f32_16x16x32_bf16 v[56:59], v[186:189], v[158:161], v[56:59]
	v_mfma_f32_16x16x32_bf16 v[52:55], v[190:193], v[158:161], v[52:55]
	v_mfma_f32_16x16x32_bf16 v[48:51], v[194:197], v[158:161], v[48:51]
	s_setprio 0
	ds_read_b64 v[158:159], v181 offset:1040
	ds_read_b64 v[160:161], v181 offset:1072
	ds_read_b64 v[166:167], v218 offset:1296
	ds_read_b64 v[168:169], v218 offset:1328
	ds_read_b64 v[170:171], v219 offset:1552
	ds_read_b64 v[172:173], v219 offset:1584
	ds_read_b64 v[174:175], v220 offset:1040
	ds_read_b64 v[176:177], v220 offset:1072
	ds_read_b128 v[182:185], v119 offset:3456
	ds_read_b128 v[186:189], v119 offset:3520
	ds_read_b128 v[190:193], v119 offset:5760
	ds_read_b128 v[194:197], v119 offset:5824
	v_add_u32_e32 v136, s60, v156
	v_add_u32_sdwa v165, s60, v141 dst_sel:DWORD dst_unused:UNUSED_PAD src0_sel:DWORD src1_sel:BYTE_2
	v_add_u32_sdwa v163, s60, v140 dst_sel:DWORD dst_unused:UNUSED_PAD src0_sel:DWORD src1_sel:BYTE_1
	v_add_u32_sdwa v215, s60, v141 dst_sel:DWORD dst_unused:UNUSED_PAD src0_sel:DWORD src1_sel:BYTE_3
	ds_read_b32 v136, v136 offset:41856
	ds_read_b32 v223, v163 offset:41856
	ds_read_b32 v165, v165 offset:41856
	ds_read_b32 v224, v215 offset:41856
	s_setprio 1
	s_waitcnt vmcnt(5)
	v_mfma_f32_16x16x32_bf16 v[198:201], v[198:201], v[88:91], 0
	s_waitcnt vmcnt(4)
	v_mfma_f32_16x16x32_bf16 v[198:201], v[202:205], v[92:95], v[198:201]
	v_mfma_f32_16x16x32_bf16 v[202:205], v[206:209], v[88:91], 0
	v_mfma_f32_16x16x32_bf16 v[202:205], v[210:213], v[92:95], v[202:205]
	s_setprio 0
	s_nop 6
	v_cndmask_b32_e64 v163, v198, v202, s[16:17]
	s_waitcnt lgkmcnt(15)
	v_add_f32_e32 v163, v217, v163
	v_cndmask_b32_e64 v198, v199, v203, s[18:19]
	v_cndmask_b32_e64 v200, v200, v204, s[6:7]
	v_exp_f32_e32 v163, v163
	v_add_f32_e32 v179, v179, v198
	s_waitcnt lgkmcnt(15)
	v_add_f32_e32 v200, v221, v200
	v_exp_f32_e32 v179, v179
	v_exp_f32_e32 v215, v200
	v_cndmask_b32_e64 v200, v201, v205, s[8:9]
	s_waitcnt lgkmcnt(15)
	v_add_f32_e32 v200, v222, v200
	v_exp_f32_e32 v217, v200
	v_cndmask_b32_e64 v198, v163, 0, s[16:17]
	v_cndmask_b32_e64 v202, 0, v163, s[16:17]
	v_pk_add_f32 v[162:163], v[162:163], 0 op_sel_hi:[1,0]
	v_cndmask_b32_e64 v199, v179, 0, s[18:19]
	v_pk_add_f32 v[162:163], v[178:179], v[162:163]
	v_cndmask_b32_e64 v200, 0, v179, s[18:19]
	v_pk_add_f32 v[162:163], v[214:215], v[162:163]
	v_cndmask_b32_e64 v201, v215, 0, s[6:7]
	v_pk_add_f32 v[162:163], v[216:217], v[162:163]
	v_cndmask_b32_e64 v203, 0, v215, s[6:7]
	v_pk_add_f32 v[130:131], v[130:131], v[162:163]
	v_cndmask_b32_e64 v204, v217, 0, s[8:9]
	v_cndmask_b32_e64 v205, 0, v217, s[8:9]
	v_cvt_pk_bf16_f32 v198, v198, v199
	v_cvt_pk_bf16_f32 v199, v201, v204
	v_cvt_pk_bf16_f32 v200, v202, v200
	v_cvt_pk_bf16_f32 v201, v203, v205
	s_setprio 1
	s_waitcnt lgkmcnt(14)
	v_mfma_f32_16x16x32_bf16 v[44:47], v[158:161], v[198:201], v[44:47]
	s_waitcnt lgkmcnt(12)
	v_mfma_f32_16x16x32_bf16 v[40:43], v[166:169], v[198:201], v[40:43]
	s_waitcnt lgkmcnt(10)
	v_mfma_f32_16x16x32_bf16 v[36:39], v[170:173], v[198:201], v[36:39]
	s_waitcnt lgkmcnt(8)
	v_mfma_f32_16x16x32_bf16 v[32:35], v[174:177], v[198:201], v[32:35]
	s_setprio 0
	ds_read_b64 v[158:159], v181 offset:1072
	ds_read_b64 v[160:161], v181 offset:1104
	ds_read_b64 v[166:167], v218 offset:1328
	ds_read_b64 v[168:169], v218 offset:1360
	ds_read_b64 v[170:171], v219 offset:1584
	ds_read_b64 v[172:173], v219 offset:1616
	ds_read_b64 v[174:175], v220 offset:1072
	ds_read_b64 v[176:177], v220 offset:1104
	ds_read_b128 v[198:201], v119 offset:4608
	ds_read_b128 v[202:205], v119 offset:4672
	v_add_u32_e32 v119, v148, v151
	ds_read_b128 v[206:209], v119
	ds_read_b128 v[210:213], v119 offset:64
	v_add_u32_e32 v119, s60, v154
	v_add_u32_sdwa v162, s60, v145 dst_sel:DWORD dst_unused:UNUSED_PAD src0_sel:DWORD src1_sel:BYTE_1
	v_add_u32_sdwa v163, s60, v146 dst_sel:DWORD dst_unused:UNUSED_PAD src0_sel:DWORD src1_sel:BYTE_2
	v_add_u32_sdwa v178, s60, v146 dst_sel:DWORD dst_unused:UNUSED_PAD src0_sel:DWORD src1_sel:BYTE_3
	ds_read_b32 v119, v119 offset:41856
	ds_read_b32 v179, v162 offset:41856
	ds_read_b32 v214, v163 offset:41856
	ds_read_b32 v215, v178 offset:41856
	s_setprio 1
	s_waitcnt vmcnt(3) lgkmcnt(15)
	v_mfma_f32_16x16x32_bf16 v[182:185], v[182:185], v[96:99], 0
	s_waitcnt vmcnt(2)
	v_mfma_f32_16x16x32_bf16 v[182:185], v[186:189], v[100:103], v[182:185]
	v_mfma_f32_16x16x32_bf16 v[186:189], v[190:193], v[96:99], 0
	v_mfma_f32_16x16x32_bf16 v[186:189], v[194:197], v[100:103], v[186:189]
	s_setprio 0
	s_nop 6
	v_cndmask_b32_e64 v162, v186, v182, s[2:3]
	v_add_f32_e32 v136, v136, v162
	v_exp_f32_e32 v162, v136
	v_cndmask_b32_e64 v136, v187, v183, s[4:5]
	v_cndmask_b32_e64 v183, v184, v188, s[22:23]
	s_waitcnt lgkmcnt(15)
	v_add_f32_e32 v165, v165, v183
	v_exp_f32_e32 v190, v165
	v_cndmask_b32_e64 v165, v185, v189, s[24:25]
	v_add_f32_e32 v136, v223, v136
	s_waitcnt lgkmcnt(15)
	v_add_f32_e32 v165, v224, v165
	v_exp_f32_e32 v178, v136
	v_exp_f32_e32 v192, v165
	v_cndmask_b32_e64 v183, v190, 0, s[22:23]
	v_cndmask_b32_e64 v185, 0, v190, s[22:23]
	v_cndmask_b32_e64 v182, 0, v178, s[4:5]
	v_cndmask_b32_e64 v184, v192, 0, s[24:25]
	v_cndmask_b32_e64 v136, 0, v162, s[2:3]
	v_cndmask_b32_e64 v163, v162, 0, s[2:3]
	v_cndmask_b32_e64 v165, v178, 0, s[4:5]
	v_cndmask_b32_e64 v186, 0, v192, s[24:25]
	v_cvt_pk_bf16_f32 v182, v136, v182
	v_cvt_pk_bf16_f32 v183, v183, v184
	v_cvt_pk_bf16_f32 v184, v163, v165
	v_cvt_pk_bf16_f32 v185, v185, v186
	s_setprio 1
	s_waitcnt lgkmcnt(14)
	v_mfma_f32_16x16x32_bf16 v[28:31], v[158:161], v[182:185], v[28:31]
	s_waitcnt lgkmcnt(12)
	v_mfma_f32_16x16x32_bf16 v[24:27], v[166:169], v[182:185], v[24:27]
	s_waitcnt lgkmcnt(10)
	v_mfma_f32_16x16x32_bf16 v[20:23], v[170:173], v[182:185], v[20:23]
	s_waitcnt lgkmcnt(8)
	v_mfma_f32_16x16x32_bf16 v[16:19], v[174:177], v[182:185], v[16:19]
	s_setprio 0
	ds_read_b64 v[158:159], v220 offset:1088
	ds_read_b64 v[160:161], v220 offset:1120
	ds_read_b64 v[166:167], v219 offset:1600
	ds_read_b64 v[168:169], v219 offset:1632
	ds_read_b64 v[170:171], v218 offset:1344
	ds_read_b64 v[172:173], v218 offset:1376
	ds_read_b64 v[174:175], v181 offset:1088
	ds_read_b64 v[176:177], v181 offset:1120
	s_setprio 1
	s_waitcnt vmcnt(1) lgkmcnt(15)
	v_mfma_f32_16x16x32_bf16 v[182:185], v[198:201], v[104:107], 0
	s_waitcnt lgkmcnt(13)
	v_mfma_f32_16x16x32_bf16 v[186:189], v[206:209], v[104:107], 0
	s_waitcnt vmcnt(0)
	v_mfma_f32_16x16x32_bf16 v[182:185], v[202:205], v[108:111], v[182:185]
	s_waitcnt lgkmcnt(12)
	v_mfma_f32_16x16x32_bf16 v[186:189], v[210:213], v[108:111], v[186:189]
	s_setprio 0
	s_nop 6
	v_cndmask_b32_e64 v136, v182, v186, s[26:27]
	s_waitcnt lgkmcnt(11)
	v_add_f32_e32 v119, v119, v136
	v_exp_f32_e32 v163, v119
	v_cndmask_b32_e64 v119, v183, v187, s[28:29]
	v_cndmask_b32_e64 v181, v184, v188, s[30:31]
	s_waitcnt lgkmcnt(10)
	v_add_f32_e32 v119, v179, v119
	s_waitcnt lgkmcnt(9)
	v_add_f32_e32 v181, v214, v181
	v_exp_f32_e32 v179, v119
	v_exp_f32_e32 v191, v181
	v_cndmask_b32_e64 v181, v185, v189, s[34:35]
	s_waitcnt lgkmcnt(8)
	v_add_f32_e32 v181, v215, v181
	v_exp_f32_e32 v193, v181
	v_cndmask_b32_e64 v119, v163, 0, s[26:27]
	v_cndmask_b32_e64 v136, 0, v163, s[26:27]
	v_pk_add_f32 v[162:163], v[162:163], 0 op_sel_hi:[1,0]
	v_cndmask_b32_e64 v183, v191, 0, s[30:31]
	v_pk_add_f32 v[162:163], v[178:179], v[162:163]
	v_cndmask_b32_e64 v185, 0, v191, s[30:31]
	v_pk_add_f32 v[162:163], v[190:191], v[162:163]
	v_cndmask_b32_e64 v184, v193, 0, s[34:35]
	v_pk_add_f32 v[162:163], v[192:193], v[162:163]
	v_cndmask_b32_e64 v165, v179, 0, s[28:29]
	v_pk_add_f32 v[124:125], v[124:125], v[162:163]
	v_cndmask_b32_e64 v181, 0, v179, s[28:29]
	v_cndmask_b32_e64 v186, 0, v193, s[34:35]
	v_cvt_pk_bf16_f32 v182, v119, v165
	v_cvt_pk_bf16_f32 v183, v183, v184
	v_cvt_pk_bf16_f32 v184, v136, v181
	v_cvt_pk_bf16_f32 v185, v185, v186
	s_setprio 1
	s_waitcnt lgkmcnt(0)
	v_mfma_f32_16x16x32_bf16 v[12:15], v[174:177], v[182:185], v[12:15]
	v_mfma_f32_16x16x32_bf16 v[8:11], v[170:173], v[182:185], v[8:11]
	v_mfma_f32_16x16x32_bf16 v[4:7], v[166:169], v[182:185], v[4:7]
	v_mfma_f32_16x16x32_bf16 v[0:3], v[158:161], v[182:185], v[0:3]
	s_setprio 0

.LBB0_697:
	s_add_i32 s52, s40, -2
	s_cmp_ge_u32 s52, s38
	s_cselect_b64 s[62:63], -1, 0
	s_cmp_lt_u32 s52, s39
	s_cselect_b64 s[74:75], -1, 0
	s_and_b64 s[62:63], s[62:63], s[74:75]
	s_andn2_b64 vcc, exec, s[62:63]
	s_cbranch_vccnz .LBB0_699
	v_add_u32_e32 v178, v150, v149
	v_add_u32_e32 v181, 0x6800, v178
	v_add_u32_e32 v218, 0x7000, v178
	v_add_u32_e32 v219, 0x7800, v178
	v_add_u32_e32 v178, v150, v151
	v_add_u32_e32 v119, v148, v149
	v_add_u32_e32 v136, s60, v152
	v_add_u32_sdwa v163, s60, v144 dst_sel:DWORD dst_unused:UNUSED_PAD src0_sel:DWORD src1_sel:BYTE_2
	v_add_u32_sdwa v165, s60, v144 dst_sel:DWORD dst_unused:UNUSED_PAD src0_sel:DWORD src1_sel:BYTE_3
	v_add_u32_e32 v220, 0x6800, v178
	v_add_u32_sdwa v179, s60, v142 dst_sel:DWORD dst_unused:UNUSED_PAD src0_sel:DWORD src1_sel:BYTE_1
	ds_read_b128 v[158:161], v119 offset:18432
	ds_read_b128 v[166:169], v119 offset:18496
	ds_read_b128 v[170:173], v119 offset:20736
	ds_read_b128 v[174:177], v119 offset:20800
	v_add_u32_e32 v162, s60, v153
	ds_read_b64 v[182:183], v181 offset:1024
	ds_read_b64 v[184:185], v181 offset:1056
	ds_read_b64 v[186:187], v218 offset:1280
	ds_read_b64 v[188:189], v218 offset:1312
	ds_read_b64 v[190:191], v219 offset:1536
	ds_read_b64 v[192:193], v219 offset:1568
	ds_read_b64 v[194:195], v220 offset:1024
	ds_read_b64 v[196:197], v220 offset:1056
	ds_read_b128 v[198:201], v119 offset:19584
	ds_read_b128 v[202:205], v119 offset:19648
	ds_read_b128 v[206:209], v119 offset:21888
	ds_read_b128 v[210:213], v119 offset:21952
	v_add_u32_e32 v178, s60, v155
	v_add_u32_sdwa v214, s60, v143 dst_sel:DWORD dst_unused:UNUSED_PAD src0_sel:DWORD src1_sel:BYTE_2
	v_add_u32_sdwa v215, s60, v143 dst_sel:DWORD dst_unused:UNUSED_PAD src0_sel:DWORD src1_sel:BYTE_3
	ds_read_b32 v136, v136 offset:41984
	ds_read_b32 v216, v162 offset:41984
	ds_read_b32 v163, v163 offset:41984
	ds_read_b32 v165, v165 offset:41984
	ds_read_b32 v217, v178 offset:41984
	ds_read_b32 v179, v179 offset:41984
	ds_read_b32 v221, v214 offset:41984
	ds_read_b32 v222, v215 offset:41984
	s_setprio 1
	s_waitcnt vmcnt(7) lgkmcnt(15)
	v_mfma_f32_16x16x32_bf16 v[158:161], v[158:161], v[80:83], 0
	s_waitcnt vmcnt(6)
	v_mfma_f32_16x16x32_bf16 v[158:161], v[166:169], v[84:87], v[158:161]
	v_mfma_f32_16x16x32_bf16 v[166:169], v[170:173], v[80:83], 0
	v_mfma_f32_16x16x32_bf16 v[166:169], v[174:177], v[84:87], v[166:169]
	s_setprio 0
	s_nop 6
	v_cndmask_b32_e64 v158, v166, v158, s[20:21]
	s_waitcnt lgkmcnt(7)
	v_add_f32_e32 v136, v136, v158
	v_exp_f32_e32 v162, v136
	v_cndmask_b32_e64 v136, v159, v167, s[10:11]
	v_cndmask_b32_e64 v159, v160, v168, s[12:13]
	s_waitcnt lgkmcnt(5)
	v_add_f32_e32 v159, v163, v159
	v_add_f32_e32 v136, v216, v136
	v_exp_f32_e32 v214, v159
	v_cndmask_b32_e64 v159, v161, v169, s[14:15]
	v_exp_f32_e32 v178, v136
	s_waitcnt lgkmcnt(4)
	v_add_f32_e32 v159, v165, v159
	v_exp_f32_e32 v216, v159
	v_cndmask_b32_e64 v159, v214, 0, s[12:13]
	v_cndmask_b32_e64 v158, v178, 0, s[10:11]
	v_cndmask_b32_e64 v160, 0, v178, s[10:11]
	v_cndmask_b32_e64 v161, 0, v214, s[12:13]
	v_cndmask_b32_e64 v136, 0, v162, s[20:21]
	v_cndmask_b32_e64 v166, v162, 0, s[20:21]
	v_cndmask_b32_e64 v163, v216, 0, s[14:15]
	v_cndmask_b32_e64 v165, 0, v216, s[14:15]
	v_cvt_pk_bf16_f32 v158, v136, v158
	v_cvt_pk_bf16_f32 v159, v159, v163
	v_cvt_pk_bf16_f32 v160, v166, v160
	v_cvt_pk_bf16_f32 v161, v161, v165
	s_setprio 1
	v_mfma_f32_16x16x32_bf16 v[60:63], v[182:185], v[158:161], v[60:63]
	v_mfma_f32_16x16x32_bf16 v[56:59], v[186:189], v[158:161], v[56:59]
	v_mfma_f32_16x16x32_bf16 v[52:55], v[190:193], v[158:161], v[52:55]
	v_mfma_f32_16x16x32_bf16 v[48:51], v[194:197], v[158:161], v[48:51]
	s_setprio 0
	ds_read_b64 v[158:159], v181 offset:1040
	ds_read_b64 v[160:161], v181 offset:1072
	ds_read_b64 v[166:167], v218 offset:1296
	ds_read_b64 v[168:169], v218 offset:1328
	ds_read_b64 v[170:171], v219 offset:1552
	ds_read_b64 v[172:173], v219 offset:1584
	ds_read_b64 v[174:175], v220 offset:1040
	ds_read_b64 v[176:177], v220 offset:1072
	ds_read_b128 v[182:185], v119 offset:21888
	ds_read_b128 v[186:189], v119 offset:21952
	ds_read_b128 v[190:193], v119 offset:24192
	ds_read_b128 v[194:197], v119 offset:24256
	v_add_u32_e32 v136, s60, v156
	v_add_u32_sdwa v165, s60, v141 dst_sel:DWORD dst_unused:UNUSED_PAD src0_sel:DWORD src1_sel:BYTE_2
	v_add_u32_sdwa v163, s60, v140 dst_sel:DWORD dst_unused:UNUSED_PAD src0_sel:DWORD src1_sel:BYTE_1
	v_add_u32_sdwa v215, s60, v141 dst_sel:DWORD dst_unused:UNUSED_PAD src0_sel:DWORD src1_sel:BYTE_3
	ds_read_b32 v136, v136 offset:41984
	ds_read_b32 v223, v163 offset:41984
	ds_read_b32 v165, v165 offset:41984
	ds_read_b32 v224, v215 offset:41984
	s_setprio 1
	s_waitcnt vmcnt(5)
	v_mfma_f32_16x16x32_bf16 v[198:201], v[198:201], v[88:91], 0
	s_waitcnt vmcnt(4)
	v_mfma_f32_16x16x32_bf16 v[198:201], v[202:205], v[92:95], v[198:201]
	v_mfma_f32_16x16x32_bf16 v[202:205], v[206:209], v[88:91], 0
	v_mfma_f32_16x16x32_bf16 v[202:205], v[210:213], v[92:95], v[202:205]
	s_setprio 0
	s_nop 6
	v_cndmask_b32_e64 v163, v198, v202, s[16:17]
	s_waitcnt lgkmcnt(15)
	v_add_f32_e32 v163, v217, v163
	v_cndmask_b32_e64 v198, v199, v203, s[18:19]
	v_cndmask_b32_e64 v200, v200, v204, s[6:7]
	v_exp_f32_e32 v163, v163
	v_add_f32_e32 v179, v179, v198
	s_waitcnt lgkmcnt(15)
	v_add_f32_e32 v200, v221, v200
	v_exp_f32_e32 v179, v179
	v_exp_f32_e32 v215, v200
	v_cndmask_b32_e64 v200, v201, v205, s[8:9]
	s_waitcnt lgkmcnt(15)
	v_add_f32_e32 v200, v222, v200
	v_exp_f32_e32 v217, v200
	v_cndmask_b32_e64 v198, v163, 0, s[16:17]
	v_cndmask_b32_e64 v202, 0, v163, s[16:17]
	v_pk_add_f32 v[162:163], v[162:163], 0 op_sel_hi:[1,0]
	v_cndmask_b32_e64 v199, v179, 0, s[18:19]
	v_pk_add_f32 v[162:163], v[178:179], v[162:163]
	v_cndmask_b32_e64 v200, 0, v179, s[18:19]
	v_pk_add_f32 v[162:163], v[214:215], v[162:163]
	v_cndmask_b32_e64 v201, v215, 0, s[6:7]
	v_pk_add_f32 v[162:163], v[216:217], v[162:163]
	v_cndmask_b32_e64 v203, 0, v215, s[6:7]
	v_pk_add_f32 v[130:131], v[130:131], v[162:163]
	v_cndmask_b32_e64 v204, v217, 0, s[8:9]
	v_cndmask_b32_e64 v205, 0, v217, s[8:9]
	v_cvt_pk_bf16_f32 v198, v198, v199
	v_cvt_pk_bf16_f32 v199, v201, v204
	v_cvt_pk_bf16_f32 v200, v202, v200
	v_cvt_pk_bf16_f32 v201, v203, v205
	s_setprio 1
	s_waitcnt lgkmcnt(14)
	v_mfma_f32_16x16x32_bf16 v[44:47], v[158:161], v[198:201], v[44:47]
	s_waitcnt lgkmcnt(12)
	v_mfma_f32_16x16x32_bf16 v[40:43], v[166:169], v[198:201], v[40:43]
	s_waitcnt lgkmcnt(10)
	v_mfma_f32_16x16x32_bf16 v[36:39], v[170:173], v[198:201], v[36:39]
	s_waitcnt lgkmcnt(8)
	v_mfma_f32_16x16x32_bf16 v[32:35], v[174:177], v[198:201], v[32:35]
	s_setprio 0
	ds_read_b64 v[158:159], v181 offset:1072
	ds_read_b64 v[160:161], v181 offset:1104
	ds_read_b64 v[166:167], v218 offset:1328
	ds_read_b64 v[168:169], v218 offset:1360
	ds_read_b64 v[170:171], v219 offset:1584
	ds_read_b64 v[172:173], v219 offset:1616
	ds_read_b64 v[174:175], v220 offset:1072
	ds_read_b64 v[176:177], v220 offset:1104
	ds_read_b128 v[198:201], v119 offset:23040
	ds_read_b128 v[202:205], v119 offset:23104
	v_add_u32_e32 v119, v148, v151
	ds_read_b128 v[206:209], v119 offset:18432
	ds_read_b128 v[210:213], v119 offset:18496
	v_add_u32_e32 v119, s60, v154
	v_add_u32_sdwa v162, s60, v145 dst_sel:DWORD dst_unused:UNUSED_PAD src0_sel:DWORD src1_sel:BYTE_1
	v_add_u32_sdwa v163, s60, v146 dst_sel:DWORD dst_unused:UNUSED_PAD src0_sel:DWORD src1_sel:BYTE_2
	v_add_u32_sdwa v178, s60, v146 dst_sel:DWORD dst_unused:UNUSED_PAD src0_sel:DWORD src1_sel:BYTE_3
	ds_read_b32 v119, v119 offset:41984
	ds_read_b32 v179, v162 offset:41984
	ds_read_b32 v214, v163 offset:41984
	ds_read_b32 v215, v178 offset:41984
	s_setprio 1
	s_waitcnt vmcnt(3) lgkmcnt(15)
	v_mfma_f32_16x16x32_bf16 v[182:185], v[182:185], v[96:99], 0
	s_waitcnt vmcnt(2)
	v_mfma_f32_16x16x32_bf16 v[182:185], v[186:189], v[100:103], v[182:185]
	v_mfma_f32_16x16x32_bf16 v[186:189], v[190:193], v[96:99], 0
	v_mfma_f32_16x16x32_bf16 v[186:189], v[194:197], v[100:103], v[186:189]
	s_setprio 0
	s_nop 6
	v_cndmask_b32_e64 v162, v186, v182, s[2:3]
	v_add_f32_e32 v136, v136, v162
	v_exp_f32_e32 v162, v136
	v_cndmask_b32_e64 v136, v187, v183, s[4:5]
	v_cndmask_b32_e64 v183, v184, v188, s[22:23]
	s_waitcnt lgkmcnt(15)
	v_add_f32_e32 v165, v165, v183
	v_exp_f32_e32 v190, v165
	v_cndmask_b32_e64 v165, v185, v189, s[24:25]
	v_add_f32_e32 v136, v223, v136
	s_waitcnt lgkmcnt(15)
	v_add_f32_e32 v165, v224, v165
	v_exp_f32_e32 v178, v136
	v_exp_f32_e32 v192, v165
	v_cndmask_b32_e64 v183, v190, 0, s[22:23]
	v_cndmask_b32_e64 v185, 0, v190, s[22:23]
	v_cndmask_b32_e64 v182, 0, v178, s[4:5]
	v_cndmask_b32_e64 v184, v192, 0, s[24:25]
	v_cndmask_b32_e64 v136, 0, v162, s[2:3]
	v_cndmask_b32_e64 v163, v162, 0, s[2:3]
	v_cndmask_b32_e64 v165, v178, 0, s[4:5]
	v_cndmask_b32_e64 v186, 0, v192, s[24:25]
	v_cvt_pk_bf16_f32 v182, v136, v182
	v_cvt_pk_bf16_f32 v183, v183, v184
	v_cvt_pk_bf16_f32 v184, v163, v165
	v_cvt_pk_bf16_f32 v185, v185, v186
	s_setprio 1
	s_waitcnt lgkmcnt(14)
	v_mfma_f32_16x16x32_bf16 v[28:31], v[158:161], v[182:185], v[28:31]
	s_waitcnt lgkmcnt(12)
	v_mfma_f32_16x16x32_bf16 v[24:27], v[166:169], v[182:185], v[24:27]
	s_waitcnt lgkmcnt(10)
	v_mfma_f32_16x16x32_bf16 v[20:23], v[170:173], v[182:185], v[20:23]
	s_waitcnt lgkmcnt(8)
	v_mfma_f32_16x16x32_bf16 v[16:19], v[174:177], v[182:185], v[16:19]
	s_setprio 0
	ds_read_b64 v[158:159], v220 offset:1088
	ds_read_b64 v[160:161], v220 offset:1120
	ds_read_b64 v[166:167], v219 offset:1600
	ds_read_b64 v[168:169], v219 offset:1632
	ds_read_b64 v[170:171], v218 offset:1344
	ds_read_b64 v[172:173], v218 offset:1376
	ds_read_b64 v[174:175], v181 offset:1088
	ds_read_b64 v[176:177], v181 offset:1120
	s_setprio 1
	s_waitcnt vmcnt(1) lgkmcnt(15)
	v_mfma_f32_16x16x32_bf16 v[182:185], v[198:201], v[104:107], 0
	s_waitcnt lgkmcnt(13)
	v_mfma_f32_16x16x32_bf16 v[186:189], v[206:209], v[104:107], 0
	s_waitcnt vmcnt(0)
	v_mfma_f32_16x16x32_bf16 v[182:185], v[202:205], v[108:111], v[182:185]
	s_waitcnt lgkmcnt(12)
	v_mfma_f32_16x16x32_bf16 v[186:189], v[210:213], v[108:111], v[186:189]
	s_setprio 0
	s_nop 6
	v_cndmask_b32_e64 v136, v182, v186, s[26:27]
	s_waitcnt lgkmcnt(11)
	v_add_f32_e32 v119, v119, v136
	v_exp_f32_e32 v163, v119
	v_cndmask_b32_e64 v119, v183, v187, s[28:29]
	v_cndmask_b32_e64 v181, v184, v188, s[30:31]
	s_waitcnt lgkmcnt(10)
	v_add_f32_e32 v119, v179, v119
	s_waitcnt lgkmcnt(9)
	v_add_f32_e32 v181, v214, v181
	v_exp_f32_e32 v179, v119
	v_exp_f32_e32 v191, v181
	v_cndmask_b32_e64 v181, v185, v189, s[34:35]
	s_waitcnt lgkmcnt(8)
	v_add_f32_e32 v181, v215, v181
	v_exp_f32_e32 v193, v181
	v_cndmask_b32_e64 v119, v163, 0, s[26:27]
	v_cndmask_b32_e64 v136, 0, v163, s[26:27]
	v_pk_add_f32 v[162:163], v[162:163], 0 op_sel_hi:[1,0]
	v_cndmask_b32_e64 v183, v191, 0, s[30:31]
	v_pk_add_f32 v[162:163], v[178:179], v[162:163]
	v_cndmask_b32_e64 v185, 0, v191, s[30:31]
	v_pk_add_f32 v[162:163], v[190:191], v[162:163]
	v_cndmask_b32_e64 v184, v193, 0, s[34:35]
	v_pk_add_f32 v[162:163], v[192:193], v[162:163]
	v_cndmask_b32_e64 v165, v179, 0, s[28:29]
	v_pk_add_f32 v[124:125], v[124:125], v[162:163]
	v_cndmask_b32_e64 v181, 0, v179, s[28:29]
	v_cndmask_b32_e64 v186, 0, v193, s[34:35]
	v_cvt_pk_bf16_f32 v182, v119, v165
	v_cvt_pk_bf16_f32 v183, v183, v184
	v_cvt_pk_bf16_f32 v184, v136, v181
	v_cvt_pk_bf16_f32 v185, v185, v186
	s_setprio 1
	s_waitcnt lgkmcnt(0)
	v_mfma_f32_16x16x32_bf16 v[12:15], v[174:177], v[182:185], v[12:15]
	v_mfma_f32_16x16x32_bf16 v[8:11], v[170:173], v[182:185], v[8:11]
	v_mfma_f32_16x16x32_bf16 v[4:7], v[166:169], v[182:185], v[4:7]
	v_mfma_f32_16x16x32_bf16 v[0:3], v[158:161], v[182:185], v[0:3]
	s_setprio 0
